# mod GEMV items permuted so each XCD reads one layer's w_mod (fewer distinct pages per XCD)
# baseline (speedup 1.0000x reference)
; __device__ __forceinline__ void prologue_phase(const Args& a, LAS unsigned char* lds, int tid, int lane, int wave, int vcu, int G, bool late_w) {
;     ...
;         const float* wmod = (const float*)a.in[3]; const float* bmod = (const float*)a.in[4]; float* mod = (float*)(ws + WS_MOD);
;         for (int item = blockIdx.x; item < 4 * 48; item += G) {
;             const int l = item / 48, n0 = (item % 48) * 256;
;             const float* W = wmod + (size_t)l * D * MODW + n0 + 4 * lane;
;             f32x4 acc[8];
; #pragma unroll
;             for (int b = 0; b < 8; ++b) acc[b] = (f32x4){0.f, 0.f, 0.f, 0.f};
;             for (int kk = 0; kk < 256; kk += 8) {
;                 f32x4 w[8];
.LBB0_18:
	s_or_b64 exec, exec, s[4:5]
	v_and_b32_e32 v39, 63, v38
	s_cmpk_gt_i32 s2, 0xbf
	s_waitcnt lgkmcnt(0)
	s_barrier
	s_cbranch_scc1 .LBB0_23
	s_load_dwordx4 s[4:7], s[50:51], 0x18
	v_readlane_b32 s16, v255, 8
	v_ashrrev_i32_e32 v60, 6, v38
	s_lshl_b32 s1, s16, 13
	s_add_i32 s14, 0, 0x10000
	v_lshlrev_b32_e32 v40, 4, v39
	v_lshlrev_b32_e32 v3, 10, v60
	s_lshl_b32 s0, s16, 8
	s_add_i32 s15, s14, s1
	v_add3_u32 v61, s14, v3, v40
	s_mul_i32 s14, s16, 0xc00000
	s_mul_hi_u32 s0, s0, 0xc000
	s_waitcnt lgkmcnt(0)
	s_add_u32 s4, s4, s14
	v_lshlrev_b32_e32 v2, 2, v39
	v_mov_b32_e32 v41, 0
	s_addc_u32 s5, s5, s0
	v_add_u32_e32 v1, s15, v40
	s_mov_b32 s16, 0xc000
	v_lshl_add_u64 v[42:43], s[4:5], 0, v[40:41]
	s_add_i32 s17, s1, 0
	s_mov_b32 s18, 0x18000
	s_mov_b32 s19, 0x24000
	s_mov_b32 s20, 0x30000
	s_mov_b32 s21, 0x3c000
	s_mov_b32 s22, 0x48000
	s_mov_b32 s23, 0x54000
	s_mov_b64 s[4:5], 0x60000
	v_lshlrev_b32_e32 v40, 2, v2
	s_mov_b32 s24, s2
	s_cmpk_lg_i32 s86, 0x100
	s_cbranch_scc1 .Lgemv_perm_done
	s_and_b32 s0, s2, 7
	s_mul_i32 s0, s0, 24
	s_lshr_b32 s24, s2, 3
	s_add_i32 s24, s24, s0
.Lgemv_perm_done:
.LBB0_20:
	s_mul_hi_i32 s0, s24, 0x2aaaaaab
	s_lshr_b32 s1, s0, 31
	s_ashr_i32 s0, s0, 3
	s_add_i32 s25, s0, s1
	s_mul_i32 s0, s25, 48
	s_sub_i32 s0, s24, s0
	s_lshl_b32 s14, s0, 8
	s_ashr_i32 s15, s14, 31
	s_mul_i32 s1, s25, 0x6000000
	s_lshl_b64 s[14:15], s[14:15], 2
	s_mul_hi_i32 s0, s25, 0x6000000
	s_add_u32 s26, s1, s14
	s_addc_u32 s27, s0, s15
	v_lshl_add_u64 v[44:45], v[42:43], 0, s[26:27]
	s_mov_b32 s26, -8
	s_mov_b32 s27, s17
	v_mov_b32_e32 v2, 0
	v_mov_b32_e32 v3, v41
	v_mov_b32_e32 v4, 0
	v_mov_b32_e32 v5, v41
	v_mov_b32_e32 v6, 0
	v_mov_b32_e32 v7, v41
	v_mov_b32_e32 v8, 0
	v_mov_b32_e32 v9, v41
	v_mov_b32_e32 v14, 0
	v_mov_b32_e32 v15, v41
	v_mov_b32_e32 v16, 0
	v_mov_b32_e32 v17, v41
	v_mov_b32_e32 v18, 0
	v_mov_b32_e32 v19, v41
	v_mov_b32_e32 v20, 0
	v_mov_b32_e32 v21, v41
	v_mov_b32_e32 v10, 0
	v_mov_b32_e32 v11, v41
	v_mov_b32_e32 v12, 0
	v_mov_b32_e32 v13, v41
	v_mov_b32_e32 v22, 0
	v_mov_b32_e32 v23, v41
	v_mov_b32_e32 v24, 0
	v_mov_b32_e32 v25, v41
	v_mov_b32_e32 v26, 0
	v_mov_b32_e32 v27, v41
	v_mov_b32_e32 v28, 0
	v_mov_b32_e32 v29, v41
	v_mov_b32_e32 v30, 0
	v_mov_b32_e32 v31, v41
	v_mov_b32_e32 v32, 0
	v_mov_b32_e32 v33, v41

; __device__ __forceinline__ u32x4 pack8(const f32x4& a, const f32x4& b) { u32x4 w; w.x = cvt_pk_bf16(a[0], a[1]); w.y = cvt_pk_bf16(a[2], a[3]); w.z = cvt_pk_bf16(b[0], b[1]); w.w = cvt_pk_bf16(b[2], b[3]); return w; }
;     __device__ __forceinline__ void operator()(const f32x4 (&acc)[2][2][4][2], const Unit& u, int wr, int wc, int fr, int fq) const {
;         const int row0 = u.pm * BM + wr * 64 + fr, col0 = u.pn * BM + wc * 32 + 8 * fq;
;         const float* gp = gate + (size_t)(u.pm >> 3) * 12288 + col0;
;         f32x4 gv[2][2];
; #pragma unroll
;         for (int bj = 0; bj < 2; ++bj)
; #pragma unroll
;             for (int n = 0; n < 2; ++n) { gv[bj][n] = *(const f32x4*)(gp + bj * HALF + n * 4); if (cscale) gv[bj][n] = gv[bj][n] * *(const f32x4*)(cscale + col0 + bj * HALF + n * 4); }
;     ...
;             for (int ai = 0; ai < 2; ++ai) { u32x4 xw[4][2];
; #pragma unroll
;                 for (int m = 0; m < 4; ++m)
; #pragma unroll
;                     for (int bj = 0; bj < 2; ++bj) xw[m][bj] = *(const u32x4*)((const bf16_t*)xin + (size_t)(row0 + ai * HALF + m * 16) * 2048 + col0 + bj * HALF);
; #pragma unroll
;                 for (int m = 0; m < 4; ++m)
; #pragma unroll
;                     for (int bj = 0; bj < 2; ++bj) { const u32x4 w = xw[m][bj];
;                         const f32x4 x0 = (f32x4){__builtin_bit_cast(float, w.x << 16), __builtin_bit_cast(float, w.x & 0xffff0000u), __builtin_bit_cast(float, w.y << 16), __builtin_bit_cast(float, w.y & 0xffff0000u)};
;                         const f32x4 x1 = (f32x4){__builtin_bit_cast(float, w.z << 16), __builtin_bit_cast(float, w.z & 0xffff0000u), __builtin_bit_cast(float, w.w << 16), __builtin_bit_cast(float, w.w & 0xffff0000u)};
;                         *(u32x4*)(xout + (size_t)(row0 + ai * HALF + m * 16) * 2048 + col0 + bj * HALF) = pack8(x0 + gv[bj][0] * acc[ai][bj][m][0], x1 + gv[bj][1] * acc[ai][bj][m][1]); }
.LBB0_873:
	v_mov_b32_e32 v140, v252
	s_lshl_b32 s0, s84, 8
	v_ashrrev_i32_e32 v74, 1, v140
	s_or_b32 s0, s0, s74
	v_and_b32_e32 v74, -8, v74
	v_add_u32_e32 v138, s0, v74
	s_ashr_i32 s0, s83, 3
	s_mul_hi_i32 s1, s0, 0xc000
	s_mul_i32 s0, s0, 0xc000
	s_add_u32 s40, s55, s0
	s_addc_u32 s41, s62, s1
	s_lshl_b32 s0, s83, 8
	s_add_i32 s0, s0, s63
	v_ashrrev_i32_e32 v139, 31, v138
	v_and_or_b32 v140, v140, 15, s0
	v_lshlrev_b64 v[180:181], 1, v[138:139]
	v_ashrrev_i32_e32 v141, 31, v140
	v_lshl_add_u64 v[182:183], s[60:61], 0, v[180:181]
	v_lshlrev_b64 v[184:185], 12, v[140:141]
	v_lshl_add_u64 v[82:83], v[138:139], 2, s[40:41]
	v_lshl_add_u64 v[138:139], v[182:183], 0, v[184:185]
	global_load_dwordx4 v[90:93], v[82:83], off offset:16
	global_load_dwordx4 v[94:97], v[82:83], off
	global_load_dwordx4 v[74:77], v[82:83], off offset:528
	s_nop 0
	global_load_dwordx4 v[82:85], v[82:83], off offset:512
	s_nop 0
	global_load_dwordx4 v[196:199], v[138:139], off
	global_load_dwordx4 v[200:203], v[138:139], off offset:256
	v_or_b32_e32 v138, 16, v140
	v_ashrrev_i32_e32 v139, 31, v138
	v_lshlrev_b64 v[190:191], 12, v[138:139]
	v_lshl_add_u64 v[138:139], v[182:183], 0, v[190:191]
	global_load_dwordx4 v[166:169], v[138:139], off
	global_load_dwordx4 v[162:165], v[138:139], off offset:256
	v_or_b32_e32 v138, 32, v140
	v_ashrrev_i32_e32 v139, 31, v138
	v_lshlrev_b64 v[188:189], 12, v[138:139]
	v_lshl_add_u64 v[138:139], v[182:183], 0, v[188:189]
	global_load_dwordx4 v[158:161], v[138:139], off
	global_load_dwordx4 v[154:157], v[138:139], off offset:256
	v_or_b32_e32 v138, 48, v140
	v_ashrrev_i32_e32 v139, 31, v138
	v_lshlrev_b64 v[186:187], 12, v[138:139]
	v_lshl_add_u64 v[138:139], v[182:183], 0, v[186:187]
	global_load_dwordx4 v[150:153], v[138:139], off
	s_nop 0
	global_load_dwordx4 v[138:141], v[138:139], off offset:256
	s_mov_b64 s[40:41], 0x80000
	s_mov_b64 s[70:71], -1
	s_and_b64 vcc, exec, s[8:9]
	s_waitcnt vmcnt(0)
	v_lshlrev_b32_e32 v204, 16, v196
	v_and_b32_e32 v205, 0xffff0000, v196
	v_lshlrev_b32_e32 v196, 16, v197
	v_and_b32_e32 v197, 0xffff0000, v197
	v_lshlrev_b32_e32 v206, 16, v198
	v_and_b32_e32 v207, 0xffff0000, v198
	v_lshlrev_b32_e32 v198, 16, v199
	v_and_b32_e32 v199, 0xffff0000, v199
	v_pk_fma_f32 v[146:147], v[146:147], v[94:95], v[204:205]
	v_pk_fma_f32 v[148:149], v[148:149], v[96:97], v[196:197]
	v_pk_fma_f32 v[196:197], v[144:145], v[92:93], v[198:199]
	v_pk_fma_f32 v[144:145], v[142:143], v[90:91], v[206:207]
	v_cvt_pk_bf16_f32 v142, v146, v147
	v_lshl_add_u64 v[146:147], s[60:61], 0, v[184:185]
	v_cvt_pk_bf16_f32 v143, v148, v149
	v_cvt_pk_bf16_f32 v144, v144, v145
	v_cvt_pk_bf16_f32 v145, v196, v197
	v_lshl_add_u64 v[146:147], v[146:147], 0, v[180:181]
	global_store_dwordx4 v[146:147], v[142:145], off
	v_lshlrev_b32_e32 v148, 16, v202
	v_and_b32_e32 v149, 0xffff0000, v202
	v_lshlrev_b32_e32 v142, 16, v200
	v_and_b32_e32 v143, 0xffff0000, v200
	v_lshlrev_b32_e32 v144, 16, v201
	v_and_b32_e32 v145, 0xffff0000, v201
	v_lshlrev_b32_e32 v196, 16, v203
	v_and_b32_e32 v197, 0xffff0000, v203
	v_pk_fma_f32 v[136:137], v[136:137], v[84:85], v[144:145]
	v_pk_fma_f32 v[134:135], v[134:135], v[82:83], v[142:143]
	v_pk_fma_f32 v[142:143], v[132:133], v[76:77], v[196:197]
	v_pk_fma_f32 v[132:133], v[130:131], v[74:75], v[148:149]
	v_cvt_pk_bf16_f32 v130, v134, v135
	v_cvt_pk_bf16_f32 v131, v136, v137
	v_lshlrev_b32_e32 v134, 16, v168
	v_cvt_pk_bf16_f32 v132, v132, v133
	v_cvt_pk_bf16_f32 v133, v142, v143
	global_store_dwordx4 v[146:147], v[130:133], off offset:256
	v_and_b32_e32 v135, 0xffff0000, v168
	v_lshlrev_b32_e32 v136, 16, v169
	v_lshlrev_b32_e32 v130, 16, v166
	v_and_b32_e32 v131, 0xffff0000, v166
	v_and_b32_e32 v137, 0xffff0000, v169
	v_pk_fma_f32 v[126:127], v[126:127], v[94:95], v[130:131]
	v_lshlrev_b32_e32 v132, 16, v167
	v_and_b32_e32 v133, 0xffff0000, v167
	v_pk_fma_f32 v[130:131], v[124:125], v[92:93], v[136:137]
	v_pk_fma_f32 v[124:125], v[122:123], v[90:91], v[134:135]
	v_cvt_pk_bf16_f32 v122, v126, v127
	v_lshl_add_u64 v[126:127], s[60:61], 0, v[190:191]
	v_pk_fma_f32 v[128:129], v[128:129], v[96:97], v[132:133]
	v_lshl_add_u64 v[126:127], v[126:127], 0, v[180:181]
	v_cvt_pk_bf16_f32 v123, v128, v129
	v_cvt_pk_bf16_f32 v124, v124, v125
	v_cvt_pk_bf16_f32 v125, v130, v131
	global_store_dwordx4 v[126:127], v[122:125], off
	v_lshlrev_b32_e32 v128, 16, v164
	v_and_b32_e32 v129, 0xffff0000, v164
	v_lshlrev_b32_e32 v122, 16, v162
	v_and_b32_e32 v123, 0xffff0000, v162
	v_lshlrev_b32_e32 v124, 16, v163
	v_and_b32_e32 v125, 0xffff0000, v163
	v_lshlrev_b32_e32 v130, 16, v165
	v_and_b32_e32 v131, 0xffff0000, v165
	v_pk_fma_f32 v[120:121], v[120:121], v[84:85], v[124:125]
	v_pk_fma_f32 v[118:119], v[118:119], v[82:83], v[122:123]
	v_pk_fma_f32 v[122:123], v[116:117], v[76:77], v[130:131]
	v_pk_fma_f32 v[116:117], v[114:115], v[74:75], v[128:129]
	v_cvt_pk_bf16_f32 v114, v118, v119
	v_cvt_pk_bf16_f32 v115, v120, v121
	v_lshlrev_b32_e32 v118, 16, v160
	v_cvt_pk_bf16_f32 v116, v116, v117
	v_cvt_pk_bf16_f32 v117, v122, v123
	global_store_dwordx4 v[126:127], v[114:117], off offset:256
	v_and_b32_e32 v119, 0xffff0000, v160
	v_lshlrev_b32_e32 v120, 16, v161
	v_lshlrev_b32_e32 v114, 16, v158
	v_and_b32_e32 v115, 0xffff0000, v158
	v_and_b32_e32 v121, 0xffff0000, v161
	v_pk_fma_f32 v[110:111], v[110:111], v[94:95], v[114:115]
	v_lshlrev_b32_e32 v116, 16, v159
	v_and_b32_e32 v117, 0xffff0000, v159
	v_pk_fma_f32 v[114:115], v[108:109], v[92:93], v[120:121]
	v_pk_fma_f32 v[108:109], v[106:107], v[90:91], v[118:119]
	v_cvt_pk_bf16_f32 v106, v110, v111
	v_lshl_add_u64 v[110:111], s[60:61], 0, v[188:189]
	v_pk_fma_f32 v[112:113], v[112:113], v[96:97], v[116:117]
; __device__ __forceinline__ u32x4 pack8(const f32x4& a, const f32x4& b) { u32x4 w; w.x = cvt_pk_bf16(a[0], a[1]); w.y = cvt_pk_bf16(a[2], a[3]); w.z = cvt_pk_bf16(b[0], b[1]); w.w = cvt_pk_bf16(b[2], b[3]); return w; }
;     __device__ __forceinline__ void operator()(const f32x4 (&acc)[2][2][4][2], const Unit& u, int wr, int wc, int fr, int fq) const {
;     ...
;             for (int ai = 0; ai < 2; ++ai) { u32x4 xw[4][2];
; #pragma unroll
;                 for (int m = 0; m < 4; ++m)
; #pragma unroll
;                     for (int bj = 0; bj < 2; ++bj) xw[m][bj] = *(const u32x4*)((const bf16_t*)xin + (size_t)(row0 + ai * HALF + m * 16) * 2048 + col0 + bj * HALF);
; #pragma unroll
;                 for (int m = 0; m < 4; ++m)
; #pragma unroll
;                     for (int bj = 0; bj < 2; ++bj) { const u32x4 w = xw[m][bj];
;                         const f32x4 x0 = (f32x4){__builtin_bit_cast(float, w.x << 16), __builtin_bit_cast(float, w.x & 0xffff0000u), __builtin_bit_cast(float, w.y << 16), __builtin_bit_cast(float, w.y & 0xffff0000u)};
;                         const f32x4 x1 = (f32x4){__builtin_bit_cast(float, w.z << 16), __builtin_bit_cast(float, w.z & 0xffff0000u), __builtin_bit_cast(float, w.w << 16), __builtin_bit_cast(float, w.w & 0xffff0000u)};
;                         *(u32x4*)(xout + (size_t)(row0 + ai * HALF + m * 16) * 2048 + col0 + bj * HALF) = pack8(x0 + gv[bj][0] * acc[ai][bj][m][0], x1 + gv[bj][1] * acc[ai][bj][m][1]); }
;                 asm volatile("" ::: "memory"); }
	v_lshl_add_u64 v[110:111], v[110:111], 0, v[180:181]
	v_cvt_pk_bf16_f32 v107, v112, v113
	v_cvt_pk_bf16_f32 v108, v108, v109
	v_cvt_pk_bf16_f32 v109, v114, v115
	global_store_dwordx4 v[110:111], v[106:109], off
	v_lshlrev_b32_e32 v112, 16, v156
	v_and_b32_e32 v113, 0xffff0000, v156
	v_lshlrev_b32_e32 v106, 16, v154
	v_and_b32_e32 v107, 0xffff0000, v154
	v_lshlrev_b32_e32 v108, 16, v155
	v_and_b32_e32 v109, 0xffff0000, v155
	v_lshlrev_b32_e32 v114, 16, v157
	v_and_b32_e32 v115, 0xffff0000, v157
	v_pk_fma_f32 v[104:105], v[104:105], v[84:85], v[108:109]
	v_pk_fma_f32 v[102:103], v[102:103], v[82:83], v[106:107]
	v_pk_fma_f32 v[106:107], v[100:101], v[76:77], v[114:115]
	v_pk_fma_f32 v[100:101], v[98:99], v[74:75], v[112:113]
	v_cvt_pk_bf16_f32 v98, v102, v103
	v_cvt_pk_bf16_f32 v99, v104, v105
	v_lshlrev_b32_e32 v102, 16, v152
	v_cvt_pk_bf16_f32 v100, v100, v101
	v_cvt_pk_bf16_f32 v101, v106, v107
	global_store_dwordx4 v[110:111], v[98:101], off offset:256
	v_and_b32_e32 v103, 0xffff0000, v152
	v_lshlrev_b32_e32 v104, 16, v153
	v_lshlrev_b32_e32 v98, 16, v150
	v_and_b32_e32 v99, 0xffff0000, v150
	v_and_b32_e32 v105, 0xffff0000, v153
	v_pk_fma_f32 v[86:87], v[86:87], v[94:95], v[98:99]
	v_lshlrev_b32_e32 v100, 16, v151
	v_and_b32_e32 v101, 0xffff0000, v151
	v_pk_fma_f32 v[98:99], v[80:81], v[92:93], v[104:105]
	v_pk_fma_f32 v[80:81], v[78:79], v[90:91], v[102:103]
	v_cvt_pk_bf16_f32 v78, v86, v87
	v_lshl_add_u64 v[86:87], s[60:61], 0, v[186:187]
	v_pk_fma_f32 v[88:89], v[88:89], v[96:97], v[100:101]
	v_lshl_add_u64 v[86:87], v[86:87], 0, v[180:181]
	v_cvt_pk_bf16_f32 v79, v88, v89
	v_cvt_pk_bf16_f32 v80, v80, v81
	v_cvt_pk_bf16_f32 v81, v98, v99
	global_store_dwordx4 v[86:87], v[78:81], off
	v_lshlrev_b32_e32 v88, 16, v140
	v_and_b32_e32 v89, 0xffff0000, v140
	v_lshlrev_b32_e32 v78, 16, v138
	v_and_b32_e32 v79, 0xffff0000, v138
	v_lshlrev_b32_e32 v98, 16, v141
	v_and_b32_e32 v99, 0xffff0000, v141
	v_lshlrev_b32_e32 v80, 16, v139
	v_and_b32_e32 v81, 0xffff0000, v139
	v_pk_fma_f32 v[70:71], v[70:71], v[82:83], v[78:79]
	v_pk_fma_f32 v[78:79], v[68:69], v[76:77], v[98:99]
	v_pk_fma_f32 v[68:69], v[66:67], v[74:75], v[88:89]
	v_pk_fma_f32 v[72:73], v[72:73], v[84:85], v[80:81]
	v_cvt_pk_bf16_f32 v66, v70, v71
	v_lshl_add_u64 v[80:81], v[184:185], 0, s[40:41]
	v_cvt_pk_bf16_f32 v67, v72, v73
	v_cvt_pk_bf16_f32 v68, v68, v69
	v_cvt_pk_bf16_f32 v69, v78, v79
	global_store_dwordx4 v[86:87], v[66:69], off offset:256
	s_mov_b64 s[40:41], 0x90000
	v_lshl_add_u64 v[118:119], v[184:185], 0, s[40:41]
	v_lshl_add_u64 v[66:67], v[182:183], 0, v[80:81]
	global_load_dwordx4 v[86:89], v[66:67], off
	global_load_dwordx4 v[98:101], v[66:67], off offset:256
	v_lshl_add_u64 v[66:67], v[182:183], 0, v[118:119]
	global_load_dwordx4 v[102:105], v[66:67], off
	global_load_dwordx4 v[106:109], v[66:67], off offset:256
	s_mov_b64 s[40:41], 0xa0000
	v_lshl_add_u64 v[120:121], v[184:185], 0, s[40:41]
	v_lshl_add_u64 v[66:67], v[182:183], 0, v[120:121]
	global_load_dwordx4 v[110:113], v[66:67], off
	global_load_dwordx4 v[114:117], v[66:67], off offset:256
	v_lshl_add_u64 v[78:79], v[184:185], 0, s[30:31]
	v_lshl_add_u64 v[66:67], v[182:183], 0, v[78:79]
	global_load_dwordx4 v[70:73], v[66:67], off
	s_nop 0
	global_load_dwordx4 v[66:69], v[66:67], off offset:256
	s_waitcnt vmcnt(7)
	v_lshlrev_b32_e32 v122, 16, v86
	v_and_b32_e32 v123, 0xffff0000, v86
	v_lshlrev_b32_e32 v86, 16, v87
	v_and_b32_e32 v87, 0xffff0000, v87
	v_lshlrev_b32_e32 v124, 16, v88
	v_and_b32_e32 v125, 0xffff0000, v88
	v_lshlrev_b32_e32 v88, 16, v89
	v_and_b32_e32 v89, 0xffff0000, v89
	v_pk_fma_f32 v[62:63], v[62:63], v[94:95], v[122:123]
	v_pk_fma_f32 v[64:65], v[64:65], v[96:97], v[86:87]
	v_pk_fma_f32 v[86:87], v[60:61], v[92:93], v[88:89]
	v_pk_fma_f32 v[60:61], v[58:59], v[90:91], v[124:125]
	v_cvt_pk_bf16_f32 v58, v62, v63
	v_lshl_add_u64 v[62:63], s[60:61], 0, v[80:81]
	v_cvt_pk_bf16_f32 v59, v64, v65
	v_cvt_pk_bf16_f32 v60, v60, v61
	v_cvt_pk_bf16_f32 v61, v86, v87
	v_lshl_add_u64 v[62:63], v[62:63], 0, v[180:181]
	global_store_dwordx4 v[62:63], v[58:61], off
	s_waitcnt vmcnt(7)
	v_lshlrev_b32_e32 v64, 16, v100
	v_and_b32_e32 v65, 0xffff0000, v100
	v_lshlrev_b32_e32 v58, 16, v98
	v_and_b32_e32 v59, 0xffff0000, v98
	v_lshlrev_b32_e32 v60, 16, v99
	v_and_b32_e32 v61, 0xffff0000, v99
	v_lshlrev_b32_e32 v80, 16, v101
	v_and_b32_e32 v81, 0xffff0000, v101
	v_pk_fma_f32 v[56:57], v[56:57], v[84:85], v[60:61]
	v_pk_fma_f32 v[54:55], v[54:55], v[82:83], v[58:59]
	v_pk_fma_f32 v[58:59], v[52:53], v[76:77], v[80:81]
	v_pk_fma_f32 v[52:53], v[50:51], v[74:75], v[64:65]
	v_cvt_pk_bf16_f32 v50, v54, v55
	v_cvt_pk_bf16_f32 v51, v56, v57
	s_waitcnt vmcnt(6)
; __device__ __forceinline__ u32x4 pack8(const f32x4& a, const f32x4& b) { u32x4 w; w.x = cvt_pk_bf16(a[0], a[1]); w.y = cvt_pk_bf16(a[2], a[3]); w.z = cvt_pk_bf16(b[0], b[1]); w.w = cvt_pk_bf16(b[2], b[3]); return w; }
;     __device__ __forceinline__ void operator()(const f32x4 (&acc)[2][2][4][2], const Unit& u, int wr, int wc, int fr, int fq) const {
;     ...
;                 for (int m = 0; m < 4; ++m)
; #pragma unroll
;                     for (int bj = 0; bj < 2; ++bj) { const u32x4 w = xw[m][bj];
;                         const f32x4 x0 = (f32x4){__builtin_bit_cast(float, w.x << 16), __builtin_bit_cast(float, w.x & 0xffff0000u), __builtin_bit_cast(float, w.y << 16), __builtin_bit_cast(float, w.y & 0xffff0000u)};
;                         const f32x4 x1 = (f32x4){__builtin_bit_cast(float, w.z << 16), __builtin_bit_cast(float, w.z & 0xffff0000u), __builtin_bit_cast(float, w.w << 16), __builtin_bit_cast(float, w.w & 0xffff0000u)};
;                         *(u32x4*)(xout + (size_t)(row0 + ai * HALF + m * 16) * 2048 + col0 + bj * HALF) = pack8(x0 + gv[bj][0] * acc[ai][bj][m][0], x1 + gv[bj][1] * acc[ai][bj][m][1]); }
;                 asm volatile("" ::: "memory"); }
	v_lshlrev_b32_e32 v54, 16, v104
	v_cvt_pk_bf16_f32 v52, v52, v53
	v_cvt_pk_bf16_f32 v53, v58, v59
	global_store_dwordx4 v[62:63], v[50:53], off offset:256
	v_and_b32_e32 v55, 0xffff0000, v104
	v_lshlrev_b32_e32 v56, 16, v105
	v_lshlrev_b32_e32 v50, 16, v102
	v_and_b32_e32 v51, 0xffff0000, v102
	v_and_b32_e32 v57, 0xffff0000, v105
	v_pk_fma_f32 v[46:47], v[46:47], v[94:95], v[50:51]
	v_lshlrev_b32_e32 v52, 16, v103
	v_and_b32_e32 v53, 0xffff0000, v103
	v_pk_fma_f32 v[50:51], v[44:45], v[92:93], v[56:57]
	v_pk_fma_f32 v[44:45], v[42:43], v[90:91], v[54:55]
	v_cvt_pk_bf16_f32 v42, v46, v47
	v_lshl_add_u64 v[46:47], s[60:61], 0, v[118:119]
	v_pk_fma_f32 v[48:49], v[48:49], v[96:97], v[52:53]
	v_lshl_add_u64 v[46:47], v[46:47], 0, v[180:181]
	v_cvt_pk_bf16_f32 v43, v48, v49
	v_cvt_pk_bf16_f32 v44, v44, v45
	v_cvt_pk_bf16_f32 v45, v50, v51
	global_store_dwordx4 v[46:47], v[42:45], off
	s_waitcnt vmcnt(7)
	v_lshlrev_b32_e32 v48, 16, v108
	v_and_b32_e32 v49, 0xffff0000, v108
	v_lshlrev_b32_e32 v42, 16, v106
	v_and_b32_e32 v43, 0xffff0000, v106
	v_lshlrev_b32_e32 v44, 16, v107
	v_and_b32_e32 v45, 0xffff0000, v107
	v_lshlrev_b32_e32 v50, 16, v109
	v_and_b32_e32 v51, 0xffff0000, v109
	v_pk_fma_f32 v[40:41], v[40:41], v[84:85], v[44:45]
	v_pk_fma_f32 v[38:39], v[38:39], v[82:83], v[42:43]
	v_pk_fma_f32 v[42:43], v[36:37], v[76:77], v[50:51]
	v_pk_fma_f32 v[36:37], v[34:35], v[74:75], v[48:49]
	v_cvt_pk_bf16_f32 v34, v38, v39
	v_cvt_pk_bf16_f32 v35, v40, v41
	s_waitcnt vmcnt(6)
	v_lshlrev_b32_e32 v38, 16, v112
	v_cvt_pk_bf16_f32 v36, v36, v37
	v_cvt_pk_bf16_f32 v37, v42, v43
	global_store_dwordx4 v[46:47], v[34:37], off offset:256
	v_and_b32_e32 v39, 0xffff0000, v112
	v_lshlrev_b32_e32 v40, 16, v113
	v_lshlrev_b32_e32 v34, 16, v110
	v_and_b32_e32 v35, 0xffff0000, v110
	v_and_b32_e32 v41, 0xffff0000, v113
	v_pk_fma_f32 v[30:31], v[30:31], v[94:95], v[34:35]
	v_lshlrev_b32_e32 v36, 16, v111
	v_and_b32_e32 v37, 0xffff0000, v111
	v_pk_fma_f32 v[34:35], v[28:29], v[92:93], v[40:41]
	v_pk_fma_f32 v[28:29], v[26:27], v[90:91], v[38:39]
	v_cvt_pk_bf16_f32 v26, v30, v31
	v_lshl_add_u64 v[30:31], s[60:61], 0, v[120:121]
	v_pk_fma_f32 v[32:33], v[32:33], v[96:97], v[36:37]
	v_lshl_add_u64 v[30:31], v[30:31], 0, v[180:181]
	v_cvt_pk_bf16_f32 v27, v32, v33
	v_cvt_pk_bf16_f32 v28, v28, v29
	v_cvt_pk_bf16_f32 v29, v34, v35
	global_store_dwordx4 v[30:31], v[26:29], off
	s_waitcnt vmcnt(7)
	v_lshlrev_b32_e32 v32, 16, v116
	v_and_b32_e32 v33, 0xffff0000, v116
	v_lshlrev_b32_e32 v26, 16, v114
	v_and_b32_e32 v27, 0xffff0000, v114
	v_lshlrev_b32_e32 v28, 16, v115
	v_and_b32_e32 v29, 0xffff0000, v115
	v_lshlrev_b32_e32 v34, 16, v117
	v_and_b32_e32 v35, 0xffff0000, v117
	v_pk_fma_f32 v[24:25], v[24:25], v[84:85], v[28:29]
	v_pk_fma_f32 v[22:23], v[22:23], v[82:83], v[26:27]
	v_pk_fma_f32 v[26:27], v[20:21], v[76:77], v[34:35]
	v_pk_fma_f32 v[20:21], v[18:19], v[74:75], v[32:33]
	v_cvt_pk_bf16_f32 v18, v22, v23
	v_cvt_pk_bf16_f32 v19, v24, v25
	s_waitcnt vmcnt(6)
	v_lshlrev_b32_e32 v22, 16, v72
	v_cvt_pk_bf16_f32 v20, v20, v21
	v_cvt_pk_bf16_f32 v21, v26, v27
	global_store_dwordx4 v[30:31], v[18:21], off offset:256
	v_and_b32_e32 v23, 0xffff0000, v72
	v_lshlrev_b32_e32 v24, 16, v73
	v_lshlrev_b32_e32 v18, 16, v70
	v_and_b32_e32 v19, 0xffff0000, v70
	v_and_b32_e32 v25, 0xffff0000, v73
	v_pk_fma_f32 v[14:15], v[14:15], v[94:95], v[18:19]
	v_lshlrev_b32_e32 v20, 16, v71
	v_and_b32_e32 v21, 0xffff0000, v71
	v_pk_fma_f32 v[18:19], v[12:13], v[92:93], v[24:25]
	v_pk_fma_f32 v[12:13], v[10:11], v[90:91], v[22:23]
	v_cvt_pk_bf16_f32 v10, v14, v15
	v_lshl_add_u64 v[14:15], s[60:61], 0, v[78:79]
	v_pk_fma_f32 v[16:17], v[16:17], v[96:97], v[20:21]
	v_lshl_add_u64 v[14:15], v[14:15], 0, v[180:181]
	v_cvt_pk_bf16_f32 v11, v16, v17
	v_cvt_pk_bf16_f32 v12, v12, v13
	v_cvt_pk_bf16_f32 v13, v18, v19
	global_store_dwordx4 v[14:15], v[10:13], off
	s_waitcnt vmcnt(7)
	v_lshlrev_b32_e32 v16, 16, v68
	v_and_b32_e32 v17, 0xffff0000, v68
	v_lshlrev_b32_e32 v10, 16, v66
	v_and_b32_e32 v11, 0xffff0000, v66
	v_lshlrev_b32_e32 v18, 16, v69
	v_and_b32_e32 v19, 0xffff0000, v69
	v_lshlrev_b32_e32 v12, 16, v67
	v_and_b32_e32 v13, 0xffff0000, v67
	v_pk_fma_f32 v[6:7], v[6:7], v[82:83], v[10:11]
	v_pk_fma_f32 v[10:11], v[4:5], v[76:77], v[18:19]
	v_pk_fma_f32 v[4:5], v[2:3], v[74:75], v[16:17]
	v_pk_fma_f32 v[8:9], v[8:9], v[84:85], v[12:13]
	v_cvt_pk_bf16_f32 v2, v6, v7
	s_nop 0
	v_cvt_pk_bf16_f32 v3, v8, v9
	v_cvt_pk_bf16_f32 v4, v4, v5
	v_cvt_pk_bf16_f32 v5, v10, v11
	global_store_dwordx4 v[14:15], v[2:5], off offset:256
	s_cbranch_vccnz .LBB0_858
	s_and_b64 vcc, exec, s[6:7]
	s_cbranch_vccnz .LBB0_857
	s_barrier
	s_branch .LBB0_857

; __device__ __forceinline__ u32x4 pack8(const f32x4& a, const f32x4& b) { u32x4 w; w.x = cvt_pk_bf16(a[0], a[1]); w.y = cvt_pk_bf16(a[2], a[3]); w.z = cvt_pk_bf16(b[0], b[1]); w.w = cvt_pk_bf16(b[2], b[3]); return w; }
;     __device__ __forceinline__ void operator()(const f32x4 (&acc)[2][2][4][2], const Unit& u, int wr, int wc, int fr, int fq) const {
;         const int row0 = u.pm * BM + wr * 64 + fr, col0 = u.pn * BM + wc * 32 + 8 * fq;
;         const float* gp = gate + (size_t)(u.pm >> 3) * 12288 + col0;
;         f32x4 gv[2][2];
; #pragma unroll
;         for (int bj = 0; bj < 2; ++bj)
; #pragma unroll
;             for (int n = 0; n < 2; ++n) { gv[bj][n] = *(const f32x4*)(gp + bj * HALF + n * 4); if (cscale) gv[bj][n] = gv[bj][n] * *(const f32x4*)(cscale + col0 + bj * HALF + n * 4); }
;     ...
;             for (int ai = 0; ai < 2; ++ai) { u32x4 xw[4][2];
; #pragma unroll
;                 for (int m = 0; m < 4; ++m)
; #pragma unroll
;                     for (int bj = 0; bj < 2; ++bj) xw[m][bj] = *(const u32x4*)((const bf16_t*)xin + (size_t)(row0 + ai * HALF + m * 16) * 2048 + col0 + bj * HALF);
; #pragma unroll
;                 for (int m = 0; m < 4; ++m)
; #pragma unroll
;                     for (int bj = 0; bj < 2; ++bj) { const u32x4 w = xw[m][bj];
;                         const f32x4 x0 = (f32x4){__builtin_bit_cast(float, w.x << 16), __builtin_bit_cast(float, w.x & 0xffff0000u), __builtin_bit_cast(float, w.y << 16), __builtin_bit_cast(float, w.y & 0xffff0000u)};
;                         const f32x4 x1 = (f32x4){__builtin_bit_cast(float, w.z << 16), __builtin_bit_cast(float, w.z & 0xffff0000u), __builtin_bit_cast(float, w.w << 16), __builtin_bit_cast(float, w.w & 0xffff0000u)};
;                         *(u32x4*)(xout + (size_t)(row0 + ai * HALF + m * 16) * 2048 + col0 + bj * HALF) = pack8(x0 + gv[bj][0] * acc[ai][bj][m][0], x1 + gv[bj][1] * acc[ai][bj][m][1]); }
.LBB0_1211:
	v_mov_b32_e32 v140, v252
	s_lshl_b32 s0, s75, 8
	v_ashrrev_i32_e32 v74, 1, v140
	s_or_b32 s0, s0, s82
	v_and_b32_e32 v74, -8, v74
	v_add_u32_e32 v138, s0, v74
	s_ashr_i32 s0, s74, 3
	s_mul_hi_i32 s1, s0, 0xc000
	s_mul_i32 s0, s0, 0xc000
	s_add_u32 s0, s63, s0
	s_addc_u32 s1, s80, s1
	v_ashrrev_i32_e32 v139, 31, v138
	v_lshl_add_u64 v[82:83], v[138:139], 2, s[0:1]
	s_lshl_b32 s0, s74, 8
	s_add_i32 s0, s0, s81
	v_and_or_b32 v140, v140, 15, s0
	v_lshlrev_b64 v[180:181], 1, v[138:139]
	v_ashrrev_i32_e32 v141, 31, v140
	v_lshl_add_u64 v[182:183], s[60:61], 0, v[180:181]
	v_lshlrev_b64 v[184:185], 12, v[140:141]
	v_lshl_add_u64 v[138:139], v[182:183], 0, v[184:185]
	global_load_dwordx4 v[90:93], v[82:83], off offset:16
	global_load_dwordx4 v[94:97], v[82:83], off
	global_load_dwordx4 v[74:77], v[82:83], off offset:528
	s_nop 0
	global_load_dwordx4 v[82:85], v[82:83], off offset:512
	s_nop 0
	global_load_dwordx4 v[196:199], v[138:139], off
	global_load_dwordx4 v[200:203], v[138:139], off offset:256
	v_or_b32_e32 v138, 16, v140
	v_ashrrev_i32_e32 v139, 31, v138
	v_lshlrev_b64 v[190:191], 12, v[138:139]
	v_lshl_add_u64 v[138:139], v[182:183], 0, v[190:191]
	global_load_dwordx4 v[166:169], v[138:139], off
	global_load_dwordx4 v[162:165], v[138:139], off offset:256
	v_or_b32_e32 v138, 32, v140
	v_ashrrev_i32_e32 v139, 31, v138
	v_lshlrev_b64 v[188:189], 12, v[138:139]
	v_lshl_add_u64 v[138:139], v[182:183], 0, v[188:189]
	global_load_dwordx4 v[158:161], v[138:139], off
	global_load_dwordx4 v[154:157], v[138:139], off offset:256
	v_or_b32_e32 v138, 48, v140
	v_ashrrev_i32_e32 v139, 31, v138
	v_lshlrev_b64 v[186:187], 12, v[138:139]
	v_lshl_add_u64 v[138:139], v[182:183], 0, v[186:187]
	global_load_dwordx4 v[150:153], v[138:139], off
	s_nop 0
	global_load_dwordx4 v[138:141], v[138:139], off offset:256
	s_mov_b64 s[0:1], 0x90000
	s_mov_b64 s[74:75], -1
	s_andn2_b64 vcc, exec, s[8:9]
	s_waitcnt vmcnt(0)
	v_lshlrev_b32_e32 v204, 16, v196
	v_and_b32_e32 v205, 0xffff0000, v196
	v_lshlrev_b32_e32 v196, 16, v197
	v_and_b32_e32 v197, 0xffff0000, v197
	v_lshlrev_b32_e32 v206, 16, v198
	v_and_b32_e32 v207, 0xffff0000, v198
	v_lshlrev_b32_e32 v198, 16, v199
	v_and_b32_e32 v199, 0xffff0000, v199
	v_pk_fma_f32 v[146:147], v[146:147], v[94:95], v[204:205]
	v_pk_fma_f32 v[148:149], v[148:149], v[96:97], v[196:197]
	v_pk_fma_f32 v[196:197], v[144:145], v[92:93], v[198:199]
	v_pk_fma_f32 v[144:145], v[142:143], v[90:91], v[206:207]
	v_cvt_pk_bf16_f32 v142, v146, v147
	v_lshl_add_u64 v[146:147], s[60:61], 0, v[184:185]
	v_cvt_pk_bf16_f32 v143, v148, v149
	v_cvt_pk_bf16_f32 v144, v144, v145
	v_cvt_pk_bf16_f32 v145, v196, v197
	v_lshl_add_u64 v[146:147], v[146:147], 0, v[180:181]
	global_store_dwordx4 v[146:147], v[142:145], off
	v_lshlrev_b32_e32 v148, 16, v202
	v_and_b32_e32 v149, 0xffff0000, v202
	v_lshlrev_b32_e32 v142, 16, v200
	v_and_b32_e32 v143, 0xffff0000, v200
	v_lshlrev_b32_e32 v144, 16, v201
	v_and_b32_e32 v145, 0xffff0000, v201
	v_lshlrev_b32_e32 v196, 16, v203
	v_and_b32_e32 v197, 0xffff0000, v203
	v_pk_fma_f32 v[136:137], v[136:137], v[84:85], v[144:145]
	v_pk_fma_f32 v[134:135], v[134:135], v[82:83], v[142:143]
	v_pk_fma_f32 v[142:143], v[132:133], v[76:77], v[196:197]
	v_pk_fma_f32 v[132:133], v[130:131], v[74:75], v[148:149]
	v_cvt_pk_bf16_f32 v130, v134, v135
	v_cvt_pk_bf16_f32 v131, v136, v137
	v_lshlrev_b32_e32 v134, 16, v168
	v_cvt_pk_bf16_f32 v132, v132, v133
	v_cvt_pk_bf16_f32 v133, v142, v143
	global_store_dwordx4 v[146:147], v[130:133], off offset:256
	v_and_b32_e32 v135, 0xffff0000, v168
	v_lshlrev_b32_e32 v136, 16, v169
	v_lshlrev_b32_e32 v130, 16, v166
	v_and_b32_e32 v131, 0xffff0000, v166
	v_and_b32_e32 v137, 0xffff0000, v169
	v_pk_fma_f32 v[126:127], v[126:127], v[94:95], v[130:131]
	v_lshlrev_b32_e32 v132, 16, v167
	v_and_b32_e32 v133, 0xffff0000, v167
	v_pk_fma_f32 v[130:131], v[124:125], v[92:93], v[136:137]
	v_pk_fma_f32 v[124:125], v[122:123], v[90:91], v[134:135]
	v_cvt_pk_bf16_f32 v122, v126, v127
	v_lshl_add_u64 v[126:127], s[60:61], 0, v[190:191]
	v_pk_fma_f32 v[128:129], v[128:129], v[96:97], v[132:133]
	v_lshl_add_u64 v[126:127], v[126:127], 0, v[180:181]
	v_cvt_pk_bf16_f32 v123, v128, v129
	v_cvt_pk_bf16_f32 v124, v124, v125
	v_cvt_pk_bf16_f32 v125, v130, v131
	global_store_dwordx4 v[126:127], v[122:125], off
	v_lshlrev_b32_e32 v128, 16, v164
	v_and_b32_e32 v129, 0xffff0000, v164
	v_lshlrev_b32_e32 v122, 16, v162
	v_and_b32_e32 v123, 0xffff0000, v162
	v_lshlrev_b32_e32 v124, 16, v163
	v_and_b32_e32 v125, 0xffff0000, v163
	v_lshlrev_b32_e32 v130, 16, v165
	v_and_b32_e32 v131, 0xffff0000, v165
	v_pk_fma_f32 v[120:121], v[120:121], v[84:85], v[124:125]
	v_pk_fma_f32 v[118:119], v[118:119], v[82:83], v[122:123]
	v_pk_fma_f32 v[122:123], v[116:117], v[76:77], v[130:131]
	v_pk_fma_f32 v[116:117], v[114:115], v[74:75], v[128:129]
	v_cvt_pk_bf16_f32 v114, v118, v119
	v_cvt_pk_bf16_f32 v115, v120, v121
	v_lshlrev_b32_e32 v118, 16, v160
	v_cvt_pk_bf16_f32 v116, v116, v117
	v_cvt_pk_bf16_f32 v117, v122, v123
	global_store_dwordx4 v[126:127], v[114:117], off offset:256
	v_and_b32_e32 v119, 0xffff0000, v160
	v_lshlrev_b32_e32 v120, 16, v161
	v_lshlrev_b32_e32 v114, 16, v158
	v_and_b32_e32 v115, 0xffff0000, v158
	v_and_b32_e32 v121, 0xffff0000, v161
	v_pk_fma_f32 v[110:111], v[110:111], v[94:95], v[114:115]
	v_lshlrev_b32_e32 v116, 16, v159
	v_and_b32_e32 v117, 0xffff0000, v159
	v_pk_fma_f32 v[114:115], v[108:109], v[92:93], v[120:121]
	v_pk_fma_f32 v[108:109], v[106:107], v[90:91], v[118:119]
	v_cvt_pk_bf16_f32 v106, v110, v111
	v_lshl_add_u64 v[110:111], s[60:61], 0, v[188:189]
	v_pk_fma_f32 v[112:113], v[112:113], v[96:97], v[116:117]
; __device__ __forceinline__ u32x4 pack8(const f32x4& a, const f32x4& b) { u32x4 w; w.x = cvt_pk_bf16(a[0], a[1]); w.y = cvt_pk_bf16(a[2], a[3]); w.z = cvt_pk_bf16(b[0], b[1]); w.w = cvt_pk_bf16(b[2], b[3]); return w; }
;     __device__ __forceinline__ void operator()(const f32x4 (&acc)[2][2][4][2], const Unit& u, int wr, int wc, int fr, int fq) const {
;     ...
;             for (int ai = 0; ai < 2; ++ai) { u32x4 xw[4][2];
; #pragma unroll
;                 for (int m = 0; m < 4; ++m)
; #pragma unroll
;                     for (int bj = 0; bj < 2; ++bj) xw[m][bj] = *(const u32x4*)((const bf16_t*)xin + (size_t)(row0 + ai * HALF + m * 16) * 2048 + col0 + bj * HALF);
; #pragma unroll
;                 for (int m = 0; m < 4; ++m)
; #pragma unroll
;                     for (int bj = 0; bj < 2; ++bj) { const u32x4 w = xw[m][bj];
;                         const f32x4 x0 = (f32x4){__builtin_bit_cast(float, w.x << 16), __builtin_bit_cast(float, w.x & 0xffff0000u), __builtin_bit_cast(float, w.y << 16), __builtin_bit_cast(float, w.y & 0xffff0000u)};
;                         const f32x4 x1 = (f32x4){__builtin_bit_cast(float, w.z << 16), __builtin_bit_cast(float, w.z & 0xffff0000u), __builtin_bit_cast(float, w.w << 16), __builtin_bit_cast(float, w.w & 0xffff0000u)};
;                         *(u32x4*)(xout + (size_t)(row0 + ai * HALF + m * 16) * 2048 + col0 + bj * HALF) = pack8(x0 + gv[bj][0] * acc[ai][bj][m][0], x1 + gv[bj][1] * acc[ai][bj][m][1]); }
;                 asm volatile("" ::: "memory"); }
	v_lshl_add_u64 v[110:111], v[110:111], 0, v[180:181]
	v_cvt_pk_bf16_f32 v107, v112, v113
	v_cvt_pk_bf16_f32 v108, v108, v109
	v_cvt_pk_bf16_f32 v109, v114, v115
	global_store_dwordx4 v[110:111], v[106:109], off
	v_lshlrev_b32_e32 v112, 16, v156
	v_and_b32_e32 v113, 0xffff0000, v156
	v_lshlrev_b32_e32 v106, 16, v154
	v_and_b32_e32 v107, 0xffff0000, v154
	v_lshlrev_b32_e32 v108, 16, v155
	v_and_b32_e32 v109, 0xffff0000, v155
	v_lshlrev_b32_e32 v114, 16, v157
	v_and_b32_e32 v115, 0xffff0000, v157
	v_pk_fma_f32 v[104:105], v[104:105], v[84:85], v[108:109]
	v_pk_fma_f32 v[102:103], v[102:103], v[82:83], v[106:107]
	v_pk_fma_f32 v[106:107], v[100:101], v[76:77], v[114:115]
	v_pk_fma_f32 v[100:101], v[98:99], v[74:75], v[112:113]
	v_cvt_pk_bf16_f32 v98, v102, v103
	v_cvt_pk_bf16_f32 v99, v104, v105
	v_lshlrev_b32_e32 v102, 16, v152
	v_cvt_pk_bf16_f32 v100, v100, v101
	v_cvt_pk_bf16_f32 v101, v106, v107
	global_store_dwordx4 v[110:111], v[98:101], off offset:256
	v_and_b32_e32 v103, 0xffff0000, v152
	v_lshlrev_b32_e32 v104, 16, v153
	v_lshlrev_b32_e32 v98, 16, v150
	v_and_b32_e32 v99, 0xffff0000, v150
	v_and_b32_e32 v105, 0xffff0000, v153
	v_pk_fma_f32 v[86:87], v[86:87], v[94:95], v[98:99]
	v_lshlrev_b32_e32 v100, 16, v151
	v_and_b32_e32 v101, 0xffff0000, v151
	v_pk_fma_f32 v[98:99], v[80:81], v[92:93], v[104:105]
	v_pk_fma_f32 v[80:81], v[78:79], v[90:91], v[102:103]
	v_cvt_pk_bf16_f32 v78, v86, v87
	v_lshl_add_u64 v[86:87], s[60:61], 0, v[186:187]
	v_pk_fma_f32 v[88:89], v[88:89], v[96:97], v[100:101]
	v_lshl_add_u64 v[86:87], v[86:87], 0, v[180:181]
	v_cvt_pk_bf16_f32 v79, v88, v89
	v_cvt_pk_bf16_f32 v80, v80, v81
	v_cvt_pk_bf16_f32 v81, v98, v99
	global_store_dwordx4 v[86:87], v[78:81], off
	v_lshlrev_b32_e32 v88, 16, v140
	v_and_b32_e32 v89, 0xffff0000, v140
	v_lshlrev_b32_e32 v78, 16, v138
	v_and_b32_e32 v79, 0xffff0000, v138
	v_lshlrev_b32_e32 v98, 16, v141
	v_and_b32_e32 v99, 0xffff0000, v141
	v_lshlrev_b32_e32 v80, 16, v139
	v_and_b32_e32 v81, 0xffff0000, v139
	v_pk_fma_f32 v[70:71], v[70:71], v[82:83], v[78:79]
	v_pk_fma_f32 v[78:79], v[68:69], v[76:77], v[98:99]
	v_pk_fma_f32 v[68:69], v[66:67], v[74:75], v[88:89]
	v_pk_fma_f32 v[72:73], v[72:73], v[84:85], v[80:81]
	v_cvt_pk_bf16_f32 v66, v70, v71
	v_lshl_add_u64 v[80:81], v[184:185], 0, s[30:31]
	v_cvt_pk_bf16_f32 v67, v72, v73
	v_cvt_pk_bf16_f32 v68, v68, v69
	v_cvt_pk_bf16_f32 v69, v78, v79
	global_store_dwordx4 v[86:87], v[66:69], off offset:256
	v_lshl_add_u64 v[118:119], v[184:185], 0, s[0:1]
	s_mov_b64 s[0:1], 0xa0000
	v_lshl_add_u64 v[66:67], v[182:183], 0, v[80:81]
	global_load_dwordx4 v[86:89], v[66:67], off
	global_load_dwordx4 v[98:101], v[66:67], off offset:256
	v_lshl_add_u64 v[66:67], v[182:183], 0, v[118:119]
	global_load_dwordx4 v[102:105], v[66:67], off
	global_load_dwordx4 v[106:109], v[66:67], off offset:256
	v_lshl_add_u64 v[120:121], v[184:185], 0, s[0:1]
	v_lshl_add_u64 v[66:67], v[182:183], 0, v[120:121]
	global_load_dwordx4 v[110:113], v[66:67], off
	global_load_dwordx4 v[114:117], v[66:67], off offset:256
	s_mov_b64 s[0:1], 0xb0000
	v_lshl_add_u64 v[78:79], v[184:185], 0, s[0:1]
	v_lshl_add_u64 v[66:67], v[182:183], 0, v[78:79]
	global_load_dwordx4 v[70:73], v[66:67], off
	s_nop 0
	global_load_dwordx4 v[66:69], v[66:67], off offset:256
	s_waitcnt vmcnt(7)
	v_lshlrev_b32_e32 v122, 16, v86
	v_and_b32_e32 v123, 0xffff0000, v86
	v_lshlrev_b32_e32 v86, 16, v87
	v_and_b32_e32 v87, 0xffff0000, v87
	v_lshlrev_b32_e32 v124, 16, v88
	v_and_b32_e32 v125, 0xffff0000, v88
	v_lshlrev_b32_e32 v88, 16, v89
	v_and_b32_e32 v89, 0xffff0000, v89
	v_pk_fma_f32 v[62:63], v[62:63], v[94:95], v[122:123]
	v_pk_fma_f32 v[64:65], v[64:65], v[96:97], v[86:87]
	v_pk_fma_f32 v[86:87], v[60:61], v[92:93], v[88:89]
	v_pk_fma_f32 v[60:61], v[58:59], v[90:91], v[124:125]
	v_cvt_pk_bf16_f32 v58, v62, v63
	v_lshl_add_u64 v[62:63], s[60:61], 0, v[80:81]
	v_cvt_pk_bf16_f32 v59, v64, v65
	v_cvt_pk_bf16_f32 v60, v60, v61
	v_cvt_pk_bf16_f32 v61, v86, v87
	v_lshl_add_u64 v[62:63], v[62:63], 0, v[180:181]
	global_store_dwordx4 v[62:63], v[58:61], off
	s_waitcnt vmcnt(7)
	v_lshlrev_b32_e32 v64, 16, v100
	v_and_b32_e32 v65, 0xffff0000, v100
	v_lshlrev_b32_e32 v58, 16, v98
	v_and_b32_e32 v59, 0xffff0000, v98
	v_lshlrev_b32_e32 v60, 16, v99
	v_and_b32_e32 v61, 0xffff0000, v99
	v_lshlrev_b32_e32 v80, 16, v101
	v_and_b32_e32 v81, 0xffff0000, v101
	v_pk_fma_f32 v[56:57], v[56:57], v[84:85], v[60:61]
	v_pk_fma_f32 v[54:55], v[54:55], v[82:83], v[58:59]
	v_pk_fma_f32 v[58:59], v[52:53], v[76:77], v[80:81]
	v_pk_fma_f32 v[52:53], v[50:51], v[74:75], v[64:65]
	v_cvt_pk_bf16_f32 v50, v54, v55
	v_cvt_pk_bf16_f32 v51, v56, v57
	s_waitcnt vmcnt(6)
; __device__ __forceinline__ u32x4 pack8(const f32x4& a, const f32x4& b) { u32x4 w; w.x = cvt_pk_bf16(a[0], a[1]); w.y = cvt_pk_bf16(a[2], a[3]); w.z = cvt_pk_bf16(b[0], b[1]); w.w = cvt_pk_bf16(b[2], b[3]); return w; }
;     __device__ __forceinline__ void operator()(const f32x4 (&acc)[2][2][4][2], const Unit& u, int wr, int wc, int fr, int fq) const {
;     ...
;                 for (int m = 0; m < 4; ++m)
; #pragma unroll
;                     for (int bj = 0; bj < 2; ++bj) { const u32x4 w = xw[m][bj];
;                         const f32x4 x0 = (f32x4){__builtin_bit_cast(float, w.x << 16), __builtin_bit_cast(float, w.x & 0xffff0000u), __builtin_bit_cast(float, w.y << 16), __builtin_bit_cast(float, w.y & 0xffff0000u)};
;                         const f32x4 x1 = (f32x4){__builtin_bit_cast(float, w.z << 16), __builtin_bit_cast(float, w.z & 0xffff0000u), __builtin_bit_cast(float, w.w << 16), __builtin_bit_cast(float, w.w & 0xffff0000u)};
;                         *(u32x4*)(xout + (size_t)(row0 + ai * HALF + m * 16) * 2048 + col0 + bj * HALF) = pack8(x0 + gv[bj][0] * acc[ai][bj][m][0], x1 + gv[bj][1] * acc[ai][bj][m][1]); }
;                 asm volatile("" ::: "memory"); }
	v_lshlrev_b32_e32 v54, 16, v104
	v_cvt_pk_bf16_f32 v52, v52, v53
	v_cvt_pk_bf16_f32 v53, v58, v59
	global_store_dwordx4 v[62:63], v[50:53], off offset:256
	v_and_b32_e32 v55, 0xffff0000, v104
	v_lshlrev_b32_e32 v56, 16, v105
	v_lshlrev_b32_e32 v50, 16, v102
	v_and_b32_e32 v51, 0xffff0000, v102
	v_and_b32_e32 v57, 0xffff0000, v105
	v_pk_fma_f32 v[46:47], v[46:47], v[94:95], v[50:51]
	v_lshlrev_b32_e32 v52, 16, v103
	v_and_b32_e32 v53, 0xffff0000, v103
	v_pk_fma_f32 v[50:51], v[44:45], v[92:93], v[56:57]
	v_pk_fma_f32 v[44:45], v[42:43], v[90:91], v[54:55]
	v_cvt_pk_bf16_f32 v42, v46, v47
	v_lshl_add_u64 v[46:47], s[60:61], 0, v[118:119]
	v_pk_fma_f32 v[48:49], v[48:49], v[96:97], v[52:53]
	v_lshl_add_u64 v[46:47], v[46:47], 0, v[180:181]
	v_cvt_pk_bf16_f32 v43, v48, v49
	v_cvt_pk_bf16_f32 v44, v44, v45
	v_cvt_pk_bf16_f32 v45, v50, v51
	global_store_dwordx4 v[46:47], v[42:45], off
	s_waitcnt vmcnt(7)
	v_lshlrev_b32_e32 v48, 16, v108
	v_and_b32_e32 v49, 0xffff0000, v108
	v_lshlrev_b32_e32 v42, 16, v106
	v_and_b32_e32 v43, 0xffff0000, v106
	v_lshlrev_b32_e32 v44, 16, v107
	v_and_b32_e32 v45, 0xffff0000, v107
	v_lshlrev_b32_e32 v50, 16, v109
	v_and_b32_e32 v51, 0xffff0000, v109
	v_pk_fma_f32 v[40:41], v[40:41], v[84:85], v[44:45]
	v_pk_fma_f32 v[38:39], v[38:39], v[82:83], v[42:43]
	v_pk_fma_f32 v[42:43], v[36:37], v[76:77], v[50:51]
	v_pk_fma_f32 v[36:37], v[34:35], v[74:75], v[48:49]
	v_cvt_pk_bf16_f32 v34, v38, v39
	v_cvt_pk_bf16_f32 v35, v40, v41
	s_waitcnt vmcnt(6)
	v_lshlrev_b32_e32 v38, 16, v112
	v_cvt_pk_bf16_f32 v36, v36, v37
	v_cvt_pk_bf16_f32 v37, v42, v43
	global_store_dwordx4 v[46:47], v[34:37], off offset:256
	v_and_b32_e32 v39, 0xffff0000, v112
	v_lshlrev_b32_e32 v40, 16, v113
	v_lshlrev_b32_e32 v34, 16, v110
	v_and_b32_e32 v35, 0xffff0000, v110
	v_and_b32_e32 v41, 0xffff0000, v113
	v_pk_fma_f32 v[30:31], v[30:31], v[94:95], v[34:35]
	v_lshlrev_b32_e32 v36, 16, v111
	v_and_b32_e32 v37, 0xffff0000, v111
	v_pk_fma_f32 v[34:35], v[28:29], v[92:93], v[40:41]
	v_pk_fma_f32 v[28:29], v[26:27], v[90:91], v[38:39]
	v_cvt_pk_bf16_f32 v26, v30, v31
	v_lshl_add_u64 v[30:31], s[60:61], 0, v[120:121]
	v_pk_fma_f32 v[32:33], v[32:33], v[96:97], v[36:37]
	v_lshl_add_u64 v[30:31], v[30:31], 0, v[180:181]
	v_cvt_pk_bf16_f32 v27, v32, v33
	v_cvt_pk_bf16_f32 v28, v28, v29
	v_cvt_pk_bf16_f32 v29, v34, v35
	global_store_dwordx4 v[30:31], v[26:29], off
	s_waitcnt vmcnt(7)
	v_lshlrev_b32_e32 v32, 16, v116
	v_and_b32_e32 v33, 0xffff0000, v116
	v_lshlrev_b32_e32 v26, 16, v114
	v_and_b32_e32 v27, 0xffff0000, v114
	v_lshlrev_b32_e32 v28, 16, v115
	v_and_b32_e32 v29, 0xffff0000, v115
	v_lshlrev_b32_e32 v34, 16, v117
	v_and_b32_e32 v35, 0xffff0000, v117
	v_pk_fma_f32 v[24:25], v[24:25], v[84:85], v[28:29]
	v_pk_fma_f32 v[22:23], v[22:23], v[82:83], v[26:27]
	v_pk_fma_f32 v[26:27], v[20:21], v[76:77], v[34:35]
	v_pk_fma_f32 v[20:21], v[18:19], v[74:75], v[32:33]
	v_cvt_pk_bf16_f32 v18, v22, v23
	v_cvt_pk_bf16_f32 v19, v24, v25
	s_waitcnt vmcnt(6)
	v_lshlrev_b32_e32 v22, 16, v72
	v_cvt_pk_bf16_f32 v20, v20, v21
	v_cvt_pk_bf16_f32 v21, v26, v27
	global_store_dwordx4 v[30:31], v[18:21], off offset:256
	v_and_b32_e32 v23, 0xffff0000, v72
	v_lshlrev_b32_e32 v24, 16, v73
	v_lshlrev_b32_e32 v18, 16, v70
	v_and_b32_e32 v19, 0xffff0000, v70
	v_and_b32_e32 v25, 0xffff0000, v73
	v_pk_fma_f32 v[14:15], v[14:15], v[94:95], v[18:19]
	v_lshlrev_b32_e32 v20, 16, v71
	v_and_b32_e32 v21, 0xffff0000, v71
	v_pk_fma_f32 v[18:19], v[12:13], v[92:93], v[24:25]
	v_pk_fma_f32 v[12:13], v[10:11], v[90:91], v[22:23]
	v_cvt_pk_bf16_f32 v10, v14, v15
	v_lshl_add_u64 v[14:15], s[60:61], 0, v[78:79]
	v_pk_fma_f32 v[16:17], v[16:17], v[96:97], v[20:21]
	v_lshl_add_u64 v[14:15], v[14:15], 0, v[180:181]
	v_cvt_pk_bf16_f32 v11, v16, v17
	v_cvt_pk_bf16_f32 v12, v12, v13
	v_cvt_pk_bf16_f32 v13, v18, v19
	global_store_dwordx4 v[14:15], v[10:13], off
	s_waitcnt vmcnt(7)
	v_lshlrev_b32_e32 v16, 16, v68
	v_and_b32_e32 v17, 0xffff0000, v68
	v_lshlrev_b32_e32 v10, 16, v66
	v_and_b32_e32 v11, 0xffff0000, v66
	v_lshlrev_b32_e32 v18, 16, v69
	v_and_b32_e32 v19, 0xffff0000, v69
	v_lshlrev_b32_e32 v12, 16, v67
	v_and_b32_e32 v13, 0xffff0000, v67
	v_pk_fma_f32 v[6:7], v[6:7], v[82:83], v[10:11]
	v_pk_fma_f32 v[10:11], v[4:5], v[76:77], v[18:19]
	v_pk_fma_f32 v[4:5], v[2:3], v[74:75], v[16:17]
	v_pk_fma_f32 v[8:9], v[8:9], v[84:85], v[12:13]
	v_cvt_pk_bf16_f32 v2, v6, v7
	s_nop 0
	v_cvt_pk_bf16_f32 v3, v8, v9
	v_cvt_pk_bf16_f32 v4, v4, v5
	v_cvt_pk_bf16_f32 v5, v10, v11
	global_store_dwordx4 v[14:15], v[2:5], off offset:256
	s_cbranch_vccnz .LBB0_1200
	s_and_b64 vcc, exec, s[6:7]
	s_cbranch_vccnz .LBB0_1199
	s_barrier
	s_branch .LBB0_1199

; __device__ __forceinline__ u32x4 pack8(const f32x4& a, const f32x4& b) { u32x4 w; w.x = cvt_pk_bf16(a[0], a[1]); w.y = cvt_pk_bf16(a[2], a[3]); w.z = cvt_pk_bf16(b[0], b[1]); w.w = cvt_pk_bf16(b[2], b[3]); return w; }
;     __device__ __forceinline__ void operator()(const f32x4 (&acc)[2][2][4][2], const Unit& u, int wr, int wc, int fr, int fq) const {
;         const int row0 = u.pm * BM + wr * 64 + fr, col0 = u.pn * BM + wc * 32 + 8 * fq;
;         const float* gp = gate + (size_t)(u.pm >> 3) * 12288 + col0;
;         f32x4 gv[2][2];
; #pragma unroll
;         for (int bj = 0; bj < 2; ++bj)
; #pragma unroll
;             for (int n = 0; n < 2; ++n) { gv[bj][n] = *(const f32x4*)(gp + bj * HALF + n * 4); if (cscale) gv[bj][n] = gv[bj][n] * *(const f32x4*)(cscale + col0 + bj * HALF + n * 4); }
;     ...
;             for (int ai = 0; ai < 2; ++ai) { u32x4 xw[4][2];
; #pragma unroll
;                 for (int m = 0; m < 4; ++m)
; #pragma unroll
;                     for (int bj = 0; bj < 2; ++bj) xw[m][bj] = *(const u32x4*)((const bf16_t*)xin + (size_t)(row0 + ai * HALF + m * 16) * 2048 + col0 + bj * HALF);
; #pragma unroll
;                 for (int m = 0; m < 4; ++m)
; #pragma unroll
;                     for (int bj = 0; bj < 2; ++bj) { const u32x4 w = xw[m][bj];
;                         const f32x4 x0 = (f32x4){__builtin_bit_cast(float, w.x << 16), __builtin_bit_cast(float, w.x & 0xffff0000u), __builtin_bit_cast(float, w.y << 16), __builtin_bit_cast(float, w.y & 0xffff0000u)};
;                         const f32x4 x1 = (f32x4){__builtin_bit_cast(float, w.z << 16), __builtin_bit_cast(float, w.z & 0xffff0000u), __builtin_bit_cast(float, w.w << 16), __builtin_bit_cast(float, w.w & 0xffff0000u)};
;                         *(u32x4*)(xout + (size_t)(row0 + ai * HALF + m * 16) * 2048 + col0 + bj * HALF) = pack8(x0 + gv[bj][0] * acc[ai][bj][m][0], x1 + gv[bj][1] * acc[ai][bj][m][1]); }
.LBB0_1487:
	v_mov_b32_e32 v140, v252
	s_lshl_b32 s0, s84, 8
	v_ashrrev_i32_e32 v74, 1, v140
	s_or_b32 s0, s0, s74
	v_and_b32_e32 v74, -8, v74
	v_add_u32_e32 v138, s0, v74
	s_ashr_i32 s0, s83, 3
	s_mul_hi_i32 s1, s0, 0xc000
	s_mul_i32 s0, s0, 0xc000
	s_add_u32 s0, s55, s0
	s_addc_u32 s1, s62, s1
	v_ashrrev_i32_e32 v139, 31, v138
	v_lshl_add_u64 v[82:83], v[138:139], 2, s[0:1]
	s_lshl_b32 s0, s83, 8
	s_add_i32 s0, s0, s63
	v_and_or_b32 v140, v140, 15, s0
	v_lshlrev_b64 v[180:181], 1, v[138:139]
	v_ashrrev_i32_e32 v141, 31, v140
	v_lshl_add_u64 v[182:183], s[60:61], 0, v[180:181]
	v_lshlrev_b64 v[184:185], 12, v[140:141]
	v_lshl_add_u64 v[138:139], v[182:183], 0, v[184:185]
	global_load_dwordx4 v[90:93], v[82:83], off offset:16
	global_load_dwordx4 v[94:97], v[82:83], off
	global_load_dwordx4 v[74:77], v[82:83], off offset:528
	s_nop 0
	global_load_dwordx4 v[82:85], v[82:83], off offset:512
	s_nop 0
	global_load_dwordx4 v[196:199], v[138:139], off
	global_load_dwordx4 v[200:203], v[138:139], off offset:256
	v_or_b32_e32 v138, 16, v140
	v_ashrrev_i32_e32 v139, 31, v138
	v_lshlrev_b64 v[190:191], 12, v[138:139]
	v_lshl_add_u64 v[138:139], v[182:183], 0, v[190:191]
	global_load_dwordx4 v[166:169], v[138:139], off
	global_load_dwordx4 v[162:165], v[138:139], off offset:256
	v_or_b32_e32 v138, 32, v140
	v_ashrrev_i32_e32 v139, 31, v138
	v_lshlrev_b64 v[188:189], 12, v[138:139]
	v_lshl_add_u64 v[138:139], v[182:183], 0, v[188:189]
	global_load_dwordx4 v[158:161], v[138:139], off
	global_load_dwordx4 v[154:157], v[138:139], off offset:256
	v_or_b32_e32 v138, 48, v140
	v_ashrrev_i32_e32 v139, 31, v138
	v_lshlrev_b64 v[186:187], 12, v[138:139]
	v_lshl_add_u64 v[138:139], v[182:183], 0, v[186:187]
	global_load_dwordx4 v[150:153], v[138:139], off
	s_nop 0
	global_load_dwordx4 v[138:141], v[138:139], off offset:256
	s_mov_b64 s[0:1], 0x80000
	s_mov_b64 s[70:71], -1
	s_and_b64 vcc, exec, s[8:9]
	s_waitcnt vmcnt(0)
	v_lshlrev_b32_e32 v204, 16, v196
	v_and_b32_e32 v205, 0xffff0000, v196
	v_lshlrev_b32_e32 v196, 16, v197
	v_and_b32_e32 v197, 0xffff0000, v197
	v_lshlrev_b32_e32 v206, 16, v198
	v_and_b32_e32 v207, 0xffff0000, v198
	v_lshlrev_b32_e32 v198, 16, v199
	v_and_b32_e32 v199, 0xffff0000, v199
	v_pk_fma_f32 v[146:147], v[146:147], v[94:95], v[204:205]
	v_pk_fma_f32 v[148:149], v[148:149], v[96:97], v[196:197]
	v_pk_fma_f32 v[196:197], v[144:145], v[92:93], v[198:199]
	v_pk_fma_f32 v[144:145], v[142:143], v[90:91], v[206:207]
	v_cvt_pk_bf16_f32 v142, v146, v147
	v_lshl_add_u64 v[146:147], s[60:61], 0, v[184:185]
	v_cvt_pk_bf16_f32 v143, v148, v149
	v_cvt_pk_bf16_f32 v144, v144, v145
	v_cvt_pk_bf16_f32 v145, v196, v197
	v_lshl_add_u64 v[146:147], v[146:147], 0, v[180:181]
	global_store_dwordx4 v[146:147], v[142:145], off
	v_lshlrev_b32_e32 v148, 16, v202
	v_and_b32_e32 v149, 0xffff0000, v202
	v_lshlrev_b32_e32 v142, 16, v200
	v_and_b32_e32 v143, 0xffff0000, v200
	v_lshlrev_b32_e32 v144, 16, v201
	v_and_b32_e32 v145, 0xffff0000, v201
	v_lshlrev_b32_e32 v196, 16, v203
	v_and_b32_e32 v197, 0xffff0000, v203
	v_pk_fma_f32 v[136:137], v[136:137], v[84:85], v[144:145]
	v_pk_fma_f32 v[134:135], v[134:135], v[82:83], v[142:143]
	v_pk_fma_f32 v[142:143], v[132:133], v[76:77], v[196:197]
	v_pk_fma_f32 v[132:133], v[130:131], v[74:75], v[148:149]
	v_cvt_pk_bf16_f32 v130, v134, v135
	v_cvt_pk_bf16_f32 v131, v136, v137
	v_lshlrev_b32_e32 v134, 16, v168
	v_cvt_pk_bf16_f32 v132, v132, v133
	v_cvt_pk_bf16_f32 v133, v142, v143
	global_store_dwordx4 v[146:147], v[130:133], off offset:256
	v_and_b32_e32 v135, 0xffff0000, v168
	v_lshlrev_b32_e32 v136, 16, v169
	v_lshlrev_b32_e32 v130, 16, v166
	v_and_b32_e32 v131, 0xffff0000, v166
	v_and_b32_e32 v137, 0xffff0000, v169
	v_pk_fma_f32 v[126:127], v[126:127], v[94:95], v[130:131]
	v_lshlrev_b32_e32 v132, 16, v167
	v_and_b32_e32 v133, 0xffff0000, v167
	v_pk_fma_f32 v[130:131], v[124:125], v[92:93], v[136:137]
	v_pk_fma_f32 v[124:125], v[122:123], v[90:91], v[134:135]
	v_cvt_pk_bf16_f32 v122, v126, v127
	v_lshl_add_u64 v[126:127], s[60:61], 0, v[190:191]
	v_pk_fma_f32 v[128:129], v[128:129], v[96:97], v[132:133]
	v_lshl_add_u64 v[126:127], v[126:127], 0, v[180:181]
	v_cvt_pk_bf16_f32 v123, v128, v129
	v_cvt_pk_bf16_f32 v124, v124, v125
	v_cvt_pk_bf16_f32 v125, v130, v131
	global_store_dwordx4 v[126:127], v[122:125], off
	v_lshlrev_b32_e32 v128, 16, v164
	v_and_b32_e32 v129, 0xffff0000, v164
	v_lshlrev_b32_e32 v122, 16, v162
	v_and_b32_e32 v123, 0xffff0000, v162
	v_lshlrev_b32_e32 v124, 16, v163
	v_and_b32_e32 v125, 0xffff0000, v163
	v_lshlrev_b32_e32 v130, 16, v165
	v_and_b32_e32 v131, 0xffff0000, v165
	v_pk_fma_f32 v[120:121], v[120:121], v[84:85], v[124:125]
	v_pk_fma_f32 v[118:119], v[118:119], v[82:83], v[122:123]
	v_pk_fma_f32 v[122:123], v[116:117], v[76:77], v[130:131]
	v_pk_fma_f32 v[116:117], v[114:115], v[74:75], v[128:129]
	v_cvt_pk_bf16_f32 v114, v118, v119
	v_cvt_pk_bf16_f32 v115, v120, v121
	v_lshlrev_b32_e32 v118, 16, v160
	v_cvt_pk_bf16_f32 v116, v116, v117
	v_cvt_pk_bf16_f32 v117, v122, v123
	global_store_dwordx4 v[126:127], v[114:117], off offset:256
	v_and_b32_e32 v119, 0xffff0000, v160
	v_lshlrev_b32_e32 v120, 16, v161
	v_lshlrev_b32_e32 v114, 16, v158
	v_and_b32_e32 v115, 0xffff0000, v158
	v_and_b32_e32 v121, 0xffff0000, v161
	v_pk_fma_f32 v[110:111], v[110:111], v[94:95], v[114:115]
	v_lshlrev_b32_e32 v116, 16, v159
	v_and_b32_e32 v117, 0xffff0000, v159
	v_pk_fma_f32 v[114:115], v[108:109], v[92:93], v[120:121]
	v_pk_fma_f32 v[108:109], v[106:107], v[90:91], v[118:119]
	v_cvt_pk_bf16_f32 v106, v110, v111
	v_lshl_add_u64 v[110:111], s[60:61], 0, v[188:189]
	v_pk_fma_f32 v[112:113], v[112:113], v[96:97], v[116:117]
; __device__ __forceinline__ u32x4 pack8(const f32x4& a, const f32x4& b) { u32x4 w; w.x = cvt_pk_bf16(a[0], a[1]); w.y = cvt_pk_bf16(a[2], a[3]); w.z = cvt_pk_bf16(b[0], b[1]); w.w = cvt_pk_bf16(b[2], b[3]); return w; }
;     __device__ __forceinline__ void operator()(const f32x4 (&acc)[2][2][4][2], const Unit& u, int wr, int wc, int fr, int fq) const {
;     ...
;             for (int ai = 0; ai < 2; ++ai) { u32x4 xw[4][2];
; #pragma unroll
;                 for (int m = 0; m < 4; ++m)
; #pragma unroll
;                     for (int bj = 0; bj < 2; ++bj) xw[m][bj] = *(const u32x4*)((const bf16_t*)xin + (size_t)(row0 + ai * HALF + m * 16) * 2048 + col0 + bj * HALF);
; #pragma unroll
;                 for (int m = 0; m < 4; ++m)
; #pragma unroll
;                     for (int bj = 0; bj < 2; ++bj) { const u32x4 w = xw[m][bj];
;                         const f32x4 x0 = (f32x4){__builtin_bit_cast(float, w.x << 16), __builtin_bit_cast(float, w.x & 0xffff0000u), __builtin_bit_cast(float, w.y << 16), __builtin_bit_cast(float, w.y & 0xffff0000u)};
;                         const f32x4 x1 = (f32x4){__builtin_bit_cast(float, w.z << 16), __builtin_bit_cast(float, w.z & 0xffff0000u), __builtin_bit_cast(float, w.w << 16), __builtin_bit_cast(float, w.w & 0xffff0000u)};
;                         *(u32x4*)(xout + (size_t)(row0 + ai * HALF + m * 16) * 2048 + col0 + bj * HALF) = pack8(x0 + gv[bj][0] * acc[ai][bj][m][0], x1 + gv[bj][1] * acc[ai][bj][m][1]); }
;                 asm volatile("" ::: "memory"); }
	v_lshl_add_u64 v[110:111], v[110:111], 0, v[180:181]
	v_cvt_pk_bf16_f32 v107, v112, v113
	v_cvt_pk_bf16_f32 v108, v108, v109
	v_cvt_pk_bf16_f32 v109, v114, v115
	global_store_dwordx4 v[110:111], v[106:109], off
	v_lshlrev_b32_e32 v112, 16, v156
	v_and_b32_e32 v113, 0xffff0000, v156
	v_lshlrev_b32_e32 v106, 16, v154
	v_and_b32_e32 v107, 0xffff0000, v154
	v_lshlrev_b32_e32 v108, 16, v155
	v_and_b32_e32 v109, 0xffff0000, v155
	v_lshlrev_b32_e32 v114, 16, v157
	v_and_b32_e32 v115, 0xffff0000, v157
	v_pk_fma_f32 v[104:105], v[104:105], v[84:85], v[108:109]
	v_pk_fma_f32 v[102:103], v[102:103], v[82:83], v[106:107]
	v_pk_fma_f32 v[106:107], v[100:101], v[76:77], v[114:115]
	v_pk_fma_f32 v[100:101], v[98:99], v[74:75], v[112:113]
	v_cvt_pk_bf16_f32 v98, v102, v103
	v_cvt_pk_bf16_f32 v99, v104, v105
	v_lshlrev_b32_e32 v102, 16, v152
	v_cvt_pk_bf16_f32 v100, v100, v101
	v_cvt_pk_bf16_f32 v101, v106, v107
	global_store_dwordx4 v[110:111], v[98:101], off offset:256
	v_and_b32_e32 v103, 0xffff0000, v152
	v_lshlrev_b32_e32 v104, 16, v153
	v_lshlrev_b32_e32 v98, 16, v150
	v_and_b32_e32 v99, 0xffff0000, v150
	v_and_b32_e32 v105, 0xffff0000, v153
	v_pk_fma_f32 v[86:87], v[86:87], v[94:95], v[98:99]
	v_lshlrev_b32_e32 v100, 16, v151
	v_and_b32_e32 v101, 0xffff0000, v151
	v_pk_fma_f32 v[98:99], v[80:81], v[92:93], v[104:105]
	v_pk_fma_f32 v[80:81], v[78:79], v[90:91], v[102:103]
	v_cvt_pk_bf16_f32 v78, v86, v87
	v_lshl_add_u64 v[86:87], s[60:61], 0, v[186:187]
	v_pk_fma_f32 v[88:89], v[88:89], v[96:97], v[100:101]
	v_lshl_add_u64 v[86:87], v[86:87], 0, v[180:181]
	v_cvt_pk_bf16_f32 v79, v88, v89
	v_cvt_pk_bf16_f32 v80, v80, v81
	v_cvt_pk_bf16_f32 v81, v98, v99
	global_store_dwordx4 v[86:87], v[78:81], off
	v_lshlrev_b32_e32 v88, 16, v140
	v_and_b32_e32 v89, 0xffff0000, v140
	v_lshlrev_b32_e32 v78, 16, v138
	v_and_b32_e32 v79, 0xffff0000, v138
	v_lshlrev_b32_e32 v98, 16, v141
	v_and_b32_e32 v99, 0xffff0000, v141
	v_lshlrev_b32_e32 v80, 16, v139
	v_and_b32_e32 v81, 0xffff0000, v139
	v_pk_fma_f32 v[70:71], v[70:71], v[82:83], v[78:79]
	v_pk_fma_f32 v[78:79], v[68:69], v[76:77], v[98:99]
	v_pk_fma_f32 v[68:69], v[66:67], v[74:75], v[88:89]
	v_pk_fma_f32 v[72:73], v[72:73], v[84:85], v[80:81]
	v_cvt_pk_bf16_f32 v66, v70, v71
	v_lshl_add_u64 v[80:81], v[184:185], 0, s[0:1]
	v_cvt_pk_bf16_f32 v67, v72, v73
	v_cvt_pk_bf16_f32 v68, v68, v69
	v_cvt_pk_bf16_f32 v69, v78, v79
	global_store_dwordx4 v[86:87], v[66:69], off offset:256
	s_mov_b64 s[0:1], 0x90000
	v_lshl_add_u64 v[118:119], v[184:185], 0, s[0:1]
	v_lshl_add_u64 v[66:67], v[182:183], 0, v[80:81]
	global_load_dwordx4 v[86:89], v[66:67], off
	global_load_dwordx4 v[98:101], v[66:67], off offset:256
	v_lshl_add_u64 v[66:67], v[182:183], 0, v[118:119]
	global_load_dwordx4 v[102:105], v[66:67], off
	global_load_dwordx4 v[106:109], v[66:67], off offset:256
	s_mov_b64 s[0:1], 0xa0000
	v_lshl_add_u64 v[120:121], v[184:185], 0, s[0:1]
	v_lshl_add_u64 v[66:67], v[182:183], 0, v[120:121]
	global_load_dwordx4 v[110:113], v[66:67], off
	global_load_dwordx4 v[114:117], v[66:67], off offset:256
	v_lshl_add_u64 v[78:79], v[184:185], 0, s[30:31]
	v_lshl_add_u64 v[66:67], v[182:183], 0, v[78:79]
	global_load_dwordx4 v[70:73], v[66:67], off
	s_nop 0
	global_load_dwordx4 v[66:69], v[66:67], off offset:256
	s_waitcnt vmcnt(7)
	v_lshlrev_b32_e32 v122, 16, v86
	v_and_b32_e32 v123, 0xffff0000, v86
	v_lshlrev_b32_e32 v86, 16, v87
	v_and_b32_e32 v87, 0xffff0000, v87
	v_lshlrev_b32_e32 v124, 16, v88
	v_and_b32_e32 v125, 0xffff0000, v88
	v_lshlrev_b32_e32 v88, 16, v89
	v_and_b32_e32 v89, 0xffff0000, v89
	v_pk_fma_f32 v[62:63], v[62:63], v[94:95], v[122:123]
	v_pk_fma_f32 v[64:65], v[64:65], v[96:97], v[86:87]
	v_pk_fma_f32 v[86:87], v[60:61], v[92:93], v[88:89]
	v_pk_fma_f32 v[60:61], v[58:59], v[90:91], v[124:125]
	v_cvt_pk_bf16_f32 v58, v62, v63
	v_lshl_add_u64 v[62:63], s[60:61], 0, v[80:81]
	v_cvt_pk_bf16_f32 v59, v64, v65
	v_cvt_pk_bf16_f32 v60, v60, v61
	v_cvt_pk_bf16_f32 v61, v86, v87
	v_lshl_add_u64 v[62:63], v[62:63], 0, v[180:181]
	global_store_dwordx4 v[62:63], v[58:61], off
	s_waitcnt vmcnt(7)
	v_lshlrev_b32_e32 v64, 16, v100
	v_and_b32_e32 v65, 0xffff0000, v100
	v_lshlrev_b32_e32 v58, 16, v98
	v_and_b32_e32 v59, 0xffff0000, v98
	v_lshlrev_b32_e32 v60, 16, v99
	v_and_b32_e32 v61, 0xffff0000, v99
	v_lshlrev_b32_e32 v80, 16, v101
	v_and_b32_e32 v81, 0xffff0000, v101
	v_pk_fma_f32 v[56:57], v[56:57], v[84:85], v[60:61]
	v_pk_fma_f32 v[54:55], v[54:55], v[82:83], v[58:59]
	v_pk_fma_f32 v[58:59], v[52:53], v[76:77], v[80:81]
	v_pk_fma_f32 v[52:53], v[50:51], v[74:75], v[64:65]
	v_cvt_pk_bf16_f32 v50, v54, v55
	v_cvt_pk_bf16_f32 v51, v56, v57
	s_waitcnt vmcnt(6)
; __device__ __forceinline__ u32x4 pack8(const f32x4& a, const f32x4& b) { u32x4 w; w.x = cvt_pk_bf16(a[0], a[1]); w.y = cvt_pk_bf16(a[2], a[3]); w.z = cvt_pk_bf16(b[0], b[1]); w.w = cvt_pk_bf16(b[2], b[3]); return w; }
;     __device__ __forceinline__ void operator()(const f32x4 (&acc)[2][2][4][2], const Unit& u, int wr, int wc, int fr, int fq) const {
;     ...
;                 for (int m = 0; m < 4; ++m)
; #pragma unroll
;                     for (int bj = 0; bj < 2; ++bj) { const u32x4 w = xw[m][bj];
;                         const f32x4 x0 = (f32x4){__builtin_bit_cast(float, w.x << 16), __builtin_bit_cast(float, w.x & 0xffff0000u), __builtin_bit_cast(float, w.y << 16), __builtin_bit_cast(float, w.y & 0xffff0000u)};
;                         const f32x4 x1 = (f32x4){__builtin_bit_cast(float, w.z << 16), __builtin_bit_cast(float, w.z & 0xffff0000u), __builtin_bit_cast(float, w.w << 16), __builtin_bit_cast(float, w.w & 0xffff0000u)};
;                         *(u32x4*)(xout + (size_t)(row0 + ai * HALF + m * 16) * 2048 + col0 + bj * HALF) = pack8(x0 + gv[bj][0] * acc[ai][bj][m][0], x1 + gv[bj][1] * acc[ai][bj][m][1]); }
;                 asm volatile("" ::: "memory"); }
	v_lshlrev_b32_e32 v54, 16, v104
	v_cvt_pk_bf16_f32 v52, v52, v53
	v_cvt_pk_bf16_f32 v53, v58, v59
	global_store_dwordx4 v[62:63], v[50:53], off offset:256
	v_and_b32_e32 v55, 0xffff0000, v104
	v_lshlrev_b32_e32 v56, 16, v105
	v_lshlrev_b32_e32 v50, 16, v102
	v_and_b32_e32 v51, 0xffff0000, v102
	v_and_b32_e32 v57, 0xffff0000, v105
	v_pk_fma_f32 v[46:47], v[46:47], v[94:95], v[50:51]
	v_lshlrev_b32_e32 v52, 16, v103
	v_and_b32_e32 v53, 0xffff0000, v103
	v_pk_fma_f32 v[50:51], v[44:45], v[92:93], v[56:57]
	v_pk_fma_f32 v[44:45], v[42:43], v[90:91], v[54:55]
	v_cvt_pk_bf16_f32 v42, v46, v47
	v_lshl_add_u64 v[46:47], s[60:61], 0, v[118:119]
	v_pk_fma_f32 v[48:49], v[48:49], v[96:97], v[52:53]
	v_lshl_add_u64 v[46:47], v[46:47], 0, v[180:181]
	v_cvt_pk_bf16_f32 v43, v48, v49
	v_cvt_pk_bf16_f32 v44, v44, v45
	v_cvt_pk_bf16_f32 v45, v50, v51
	global_store_dwordx4 v[46:47], v[42:45], off
	s_waitcnt vmcnt(7)
	v_lshlrev_b32_e32 v48, 16, v108
	v_and_b32_e32 v49, 0xffff0000, v108
	v_lshlrev_b32_e32 v42, 16, v106
	v_and_b32_e32 v43, 0xffff0000, v106
	v_lshlrev_b32_e32 v44, 16, v107
	v_and_b32_e32 v45, 0xffff0000, v107
	v_lshlrev_b32_e32 v50, 16, v109
	v_and_b32_e32 v51, 0xffff0000, v109
	v_pk_fma_f32 v[40:41], v[40:41], v[84:85], v[44:45]
	v_pk_fma_f32 v[38:39], v[38:39], v[82:83], v[42:43]
	v_pk_fma_f32 v[42:43], v[36:37], v[76:77], v[50:51]
	v_pk_fma_f32 v[36:37], v[34:35], v[74:75], v[48:49]
	v_cvt_pk_bf16_f32 v34, v38, v39
	v_cvt_pk_bf16_f32 v35, v40, v41
	s_waitcnt vmcnt(6)
	v_lshlrev_b32_e32 v38, 16, v112
	v_cvt_pk_bf16_f32 v36, v36, v37
	v_cvt_pk_bf16_f32 v37, v42, v43
	global_store_dwordx4 v[46:47], v[34:37], off offset:256
	v_and_b32_e32 v39, 0xffff0000, v112
	v_lshlrev_b32_e32 v40, 16, v113
	v_lshlrev_b32_e32 v34, 16, v110
	v_and_b32_e32 v35, 0xffff0000, v110
	v_and_b32_e32 v41, 0xffff0000, v113
	v_pk_fma_f32 v[30:31], v[30:31], v[94:95], v[34:35]
	v_lshlrev_b32_e32 v36, 16, v111
	v_and_b32_e32 v37, 0xffff0000, v111
	v_pk_fma_f32 v[34:35], v[28:29], v[92:93], v[40:41]
	v_pk_fma_f32 v[28:29], v[26:27], v[90:91], v[38:39]
	v_cvt_pk_bf16_f32 v26, v30, v31
	v_lshl_add_u64 v[30:31], s[60:61], 0, v[120:121]
	v_pk_fma_f32 v[32:33], v[32:33], v[96:97], v[36:37]
	v_lshl_add_u64 v[30:31], v[30:31], 0, v[180:181]
	v_cvt_pk_bf16_f32 v27, v32, v33
	v_cvt_pk_bf16_f32 v28, v28, v29
	v_cvt_pk_bf16_f32 v29, v34, v35
	global_store_dwordx4 v[30:31], v[26:29], off
	s_waitcnt vmcnt(7)
	v_lshlrev_b32_e32 v32, 16, v116
	v_and_b32_e32 v33, 0xffff0000, v116
	v_lshlrev_b32_e32 v26, 16, v114
	v_and_b32_e32 v27, 0xffff0000, v114
	v_lshlrev_b32_e32 v28, 16, v115
	v_and_b32_e32 v29, 0xffff0000, v115
	v_lshlrev_b32_e32 v34, 16, v117
	v_and_b32_e32 v35, 0xffff0000, v117
	v_pk_fma_f32 v[24:25], v[24:25], v[84:85], v[28:29]
	v_pk_fma_f32 v[22:23], v[22:23], v[82:83], v[26:27]
	v_pk_fma_f32 v[26:27], v[20:21], v[76:77], v[34:35]
	v_pk_fma_f32 v[20:21], v[18:19], v[74:75], v[32:33]
	v_cvt_pk_bf16_f32 v18, v22, v23
	v_cvt_pk_bf16_f32 v19, v24, v25
	s_waitcnt vmcnt(6)
	v_lshlrev_b32_e32 v22, 16, v72
	v_cvt_pk_bf16_f32 v20, v20, v21
	v_cvt_pk_bf16_f32 v21, v26, v27
	global_store_dwordx4 v[30:31], v[18:21], off offset:256
	v_and_b32_e32 v23, 0xffff0000, v72
	v_lshlrev_b32_e32 v24, 16, v73
	v_lshlrev_b32_e32 v18, 16, v70
	v_and_b32_e32 v19, 0xffff0000, v70
	v_and_b32_e32 v25, 0xffff0000, v73
	v_pk_fma_f32 v[14:15], v[14:15], v[94:95], v[18:19]
	v_lshlrev_b32_e32 v20, 16, v71
	v_and_b32_e32 v21, 0xffff0000, v71
	v_pk_fma_f32 v[18:19], v[12:13], v[92:93], v[24:25]
	v_pk_fma_f32 v[12:13], v[10:11], v[90:91], v[22:23]
	v_cvt_pk_bf16_f32 v10, v14, v15
	v_lshl_add_u64 v[14:15], s[60:61], 0, v[78:79]
	v_pk_fma_f32 v[16:17], v[16:17], v[96:97], v[20:21]
	v_lshl_add_u64 v[14:15], v[14:15], 0, v[180:181]
	v_cvt_pk_bf16_f32 v11, v16, v17
	v_cvt_pk_bf16_f32 v12, v12, v13
	v_cvt_pk_bf16_f32 v13, v18, v19
	global_store_dwordx4 v[14:15], v[10:13], off
	s_waitcnt vmcnt(7)
	v_lshlrev_b32_e32 v16, 16, v68
	v_and_b32_e32 v17, 0xffff0000, v68
	v_lshlrev_b32_e32 v10, 16, v66
	v_and_b32_e32 v11, 0xffff0000, v66
	v_lshlrev_b32_e32 v18, 16, v69
	v_and_b32_e32 v19, 0xffff0000, v69
	v_lshlrev_b32_e32 v12, 16, v67
	v_and_b32_e32 v13, 0xffff0000, v67
	v_pk_fma_f32 v[6:7], v[6:7], v[82:83], v[10:11]
	v_pk_fma_f32 v[10:11], v[4:5], v[76:77], v[18:19]
	v_pk_fma_f32 v[4:5], v[2:3], v[74:75], v[16:17]
	v_pk_fma_f32 v[8:9], v[8:9], v[84:85], v[12:13]
	v_cvt_pk_bf16_f32 v2, v6, v7
	s_nop 0
	v_cvt_pk_bf16_f32 v3, v8, v9
	v_cvt_pk_bf16_f32 v4, v4, v5
	v_cvt_pk_bf16_f32 v5, v10, v11
	global_store_dwordx4 v[14:15], v[2:5], off offset:256
	s_cbranch_vccnz .LBB0_1472
	s_and_b64 vcc, exec, s[6:7]
	s_cbranch_vccnz .LBB0_1471
	s_barrier
	s_branch .LBB0_1471

; __device__ __forceinline__ u32x4 pack8(const f32x4& a, const f32x4& b) { u32x4 w; w.x = cvt_pk_bf16(a[0], a[1]); w.y = cvt_pk_bf16(a[2], a[3]); w.z = cvt_pk_bf16(b[0], b[1]); w.w = cvt_pk_bf16(b[2], b[3]); return w; }
;     __device__ __forceinline__ void operator()(const f32x4 (&acc)[2][2][4][2], const Unit& u, int wr, int wc, int fr, int fq) const {
;         const int row0 = u.pm * BM + wr * 64 + fr, col0 = u.pn * BM + wc * 32 + 8 * fq;
;         const float* gp = gate + (size_t)(u.pm >> 3) * 12288 + col0;
;         f32x4 gv[2][2];
; #pragma unroll
;         for (int bj = 0; bj < 2; ++bj)
; #pragma unroll
;             for (int n = 0; n < 2; ++n) { gv[bj][n] = *(const f32x4*)(gp + bj * HALF + n * 4); if (cscale) gv[bj][n] = gv[bj][n] * *(const f32x4*)(cscale + col0 + bj * HALF + n * 4); }
;     ...
;             for (int ai = 0; ai < 2; ++ai) { u32x4 xw[4][2];
; #pragma unroll
;                 for (int m = 0; m < 4; ++m)
; #pragma unroll
;                     for (int bj = 0; bj < 2; ++bj) xw[m][bj] = *(const u32x4*)((const bf16_t*)xin + (size_t)(row0 + ai * HALF + m * 16) * 2048 + col0 + bj * HALF);
; #pragma unroll
;                 for (int m = 0; m < 4; ++m)
; #pragma unroll
;                     for (int bj = 0; bj < 2; ++bj) { const u32x4 w = xw[m][bj];
;                         const f32x4 x0 = (f32x4){__builtin_bit_cast(float, w.x << 16), __builtin_bit_cast(float, w.x & 0xffff0000u), __builtin_bit_cast(float, w.y << 16), __builtin_bit_cast(float, w.y & 0xffff0000u)};
;                         const f32x4 x1 = (f32x4){__builtin_bit_cast(float, w.z << 16), __builtin_bit_cast(float, w.z & 0xffff0000u), __builtin_bit_cast(float, w.w << 16), __builtin_bit_cast(float, w.w & 0xffff0000u)};
;                         *(u32x4*)(xout + (size_t)(row0 + ai * HALF + m * 16) * 2048 + col0 + bj * HALF) = pack8(x0 + gv[bj][0] * acc[ai][bj][m][0], x1 + gv[bj][1] * acc[ai][bj][m][1]); }
.LBB0_2100:
	v_mov_b32_e32 v140, v252
	s_lshl_b32 s0, s73, 8
	v_ashrrev_i32_e32 v74, 1, v140
	s_or_b32 s0, s0, s80
	v_and_b32_e32 v74, -8, v74
	v_add_u32_e32 v138, s0, v74
	s_ashr_i32 s0, s72, 3
	s_mul_hi_i32 s1, s0, 0xc000
	s_mul_i32 s0, s0, 0xc000
	s_add_u32 s0, s63, s0
	s_addc_u32 s1, s78, s1
	v_ashrrev_i32_e32 v139, 31, v138
	v_lshl_add_u64 v[82:83], v[138:139], 2, s[0:1]
	s_lshl_b32 s0, s72, 8
	s_add_i32 s0, s0, s79
	v_and_or_b32 v140, v140, 15, s0
	v_lshlrev_b64 v[180:181], 1, v[138:139]
	v_ashrrev_i32_e32 v141, 31, v140
	v_lshl_add_u64 v[182:183], s[60:61], 0, v[180:181]
	v_lshlrev_b64 v[184:185], 12, v[140:141]
	v_lshl_add_u64 v[138:139], v[182:183], 0, v[184:185]
	global_load_dwordx4 v[90:93], v[82:83], off offset:16
	global_load_dwordx4 v[94:97], v[82:83], off
	global_load_dwordx4 v[74:77], v[82:83], off offset:528
	s_nop 0
	global_load_dwordx4 v[82:85], v[82:83], off offset:512
	s_nop 0
	global_load_dwordx4 v[196:199], v[138:139], off
	global_load_dwordx4 v[200:203], v[138:139], off offset:256
	v_or_b32_e32 v138, 16, v140
	v_ashrrev_i32_e32 v139, 31, v138
	v_lshlrev_b64 v[190:191], 12, v[138:139]
	v_lshl_add_u64 v[138:139], v[182:183], 0, v[190:191]
	global_load_dwordx4 v[166:169], v[138:139], off
	global_load_dwordx4 v[162:165], v[138:139], off offset:256
	v_or_b32_e32 v138, 32, v140
	v_ashrrev_i32_e32 v139, 31, v138
	v_lshlrev_b64 v[188:189], 12, v[138:139]
	v_lshl_add_u64 v[138:139], v[182:183], 0, v[188:189]
	global_load_dwordx4 v[158:161], v[138:139], off
	global_load_dwordx4 v[154:157], v[138:139], off offset:256
	v_or_b32_e32 v138, 48, v140
	v_ashrrev_i32_e32 v139, 31, v138
	v_lshlrev_b64 v[186:187], 12, v[138:139]
	v_lshl_add_u64 v[138:139], v[182:183], 0, v[186:187]
	global_load_dwordx4 v[150:153], v[138:139], off
	s_nop 0
	global_load_dwordx4 v[138:141], v[138:139], off offset:256
	s_mov_b64 s[0:1], 0x90000
	s_mov_b64 s[72:73], -1
	s_andn2_b64 vcc, exec, s[8:9]
	s_waitcnt vmcnt(0)
	v_lshlrev_b32_e32 v204, 16, v196
	v_and_b32_e32 v205, 0xffff0000, v196
	v_lshlrev_b32_e32 v196, 16, v197
	v_and_b32_e32 v197, 0xffff0000, v197
	v_lshlrev_b32_e32 v206, 16, v198
	v_and_b32_e32 v207, 0xffff0000, v198
	v_lshlrev_b32_e32 v198, 16, v199
	v_and_b32_e32 v199, 0xffff0000, v199
	v_pk_fma_f32 v[146:147], v[146:147], v[94:95], v[204:205]
	v_pk_fma_f32 v[148:149], v[148:149], v[96:97], v[196:197]
	v_pk_fma_f32 v[196:197], v[144:145], v[92:93], v[198:199]
	v_pk_fma_f32 v[144:145], v[142:143], v[90:91], v[206:207]
	v_cvt_pk_bf16_f32 v142, v146, v147
	v_lshl_add_u64 v[146:147], s[60:61], 0, v[184:185]
	v_cvt_pk_bf16_f32 v143, v148, v149
	v_cvt_pk_bf16_f32 v144, v144, v145
	v_cvt_pk_bf16_f32 v145, v196, v197
	v_lshl_add_u64 v[146:147], v[146:147], 0, v[180:181]
	global_store_dwordx4 v[146:147], v[142:145], off
	v_lshlrev_b32_e32 v148, 16, v202
	v_and_b32_e32 v149, 0xffff0000, v202
	v_lshlrev_b32_e32 v142, 16, v200
	v_and_b32_e32 v143, 0xffff0000, v200
	v_lshlrev_b32_e32 v144, 16, v201
	v_and_b32_e32 v145, 0xffff0000, v201
	v_lshlrev_b32_e32 v196, 16, v203
	v_and_b32_e32 v197, 0xffff0000, v203
	v_pk_fma_f32 v[136:137], v[136:137], v[84:85], v[144:145]
	v_pk_fma_f32 v[134:135], v[134:135], v[82:83], v[142:143]
	v_pk_fma_f32 v[142:143], v[132:133], v[76:77], v[196:197]
	v_pk_fma_f32 v[132:133], v[130:131], v[74:75], v[148:149]
	v_cvt_pk_bf16_f32 v130, v134, v135
	v_cvt_pk_bf16_f32 v131, v136, v137
	v_lshlrev_b32_e32 v134, 16, v168
	v_cvt_pk_bf16_f32 v132, v132, v133
	v_cvt_pk_bf16_f32 v133, v142, v143
	global_store_dwordx4 v[146:147], v[130:133], off offset:256
	v_and_b32_e32 v135, 0xffff0000, v168
	v_lshlrev_b32_e32 v136, 16, v169
	v_lshlrev_b32_e32 v130, 16, v166
	v_and_b32_e32 v131, 0xffff0000, v166
	v_and_b32_e32 v137, 0xffff0000, v169
	v_pk_fma_f32 v[126:127], v[126:127], v[94:95], v[130:131]
	v_lshlrev_b32_e32 v132, 16, v167
	v_and_b32_e32 v133, 0xffff0000, v167
	v_pk_fma_f32 v[130:131], v[124:125], v[92:93], v[136:137]
	v_pk_fma_f32 v[124:125], v[122:123], v[90:91], v[134:135]
	v_cvt_pk_bf16_f32 v122, v126, v127
	v_lshl_add_u64 v[126:127], s[60:61], 0, v[190:191]
	v_pk_fma_f32 v[128:129], v[128:129], v[96:97], v[132:133]
	v_lshl_add_u64 v[126:127], v[126:127], 0, v[180:181]
	v_cvt_pk_bf16_f32 v123, v128, v129
	v_cvt_pk_bf16_f32 v124, v124, v125
	v_cvt_pk_bf16_f32 v125, v130, v131
	global_store_dwordx4 v[126:127], v[122:125], off
	v_lshlrev_b32_e32 v128, 16, v164
	v_and_b32_e32 v129, 0xffff0000, v164
	v_lshlrev_b32_e32 v122, 16, v162
	v_and_b32_e32 v123, 0xffff0000, v162
	v_lshlrev_b32_e32 v124, 16, v163
	v_and_b32_e32 v125, 0xffff0000, v163
	v_lshlrev_b32_e32 v130, 16, v165
	v_and_b32_e32 v131, 0xffff0000, v165
	v_pk_fma_f32 v[120:121], v[120:121], v[84:85], v[124:125]
	v_pk_fma_f32 v[118:119], v[118:119], v[82:83], v[122:123]
	v_pk_fma_f32 v[122:123], v[116:117], v[76:77], v[130:131]
	v_pk_fma_f32 v[116:117], v[114:115], v[74:75], v[128:129]
	v_cvt_pk_bf16_f32 v114, v118, v119
	v_cvt_pk_bf16_f32 v115, v120, v121
	v_lshlrev_b32_e32 v118, 16, v160
	v_cvt_pk_bf16_f32 v116, v116, v117
	v_cvt_pk_bf16_f32 v117, v122, v123
	global_store_dwordx4 v[126:127], v[114:117], off offset:256
	v_and_b32_e32 v119, 0xffff0000, v160
	v_lshlrev_b32_e32 v120, 16, v161
	v_lshlrev_b32_e32 v114, 16, v158
	v_and_b32_e32 v115, 0xffff0000, v158
	v_and_b32_e32 v121, 0xffff0000, v161
	v_pk_fma_f32 v[110:111], v[110:111], v[94:95], v[114:115]
	v_lshlrev_b32_e32 v116, 16, v159
	v_and_b32_e32 v117, 0xffff0000, v159
	v_pk_fma_f32 v[114:115], v[108:109], v[92:93], v[120:121]
	v_pk_fma_f32 v[108:109], v[106:107], v[90:91], v[118:119]
	v_cvt_pk_bf16_f32 v106, v110, v111
	v_lshl_add_u64 v[110:111], s[60:61], 0, v[188:189]
	v_pk_fma_f32 v[112:113], v[112:113], v[96:97], v[116:117]
; __device__ __forceinline__ u32x4 pack8(const f32x4& a, const f32x4& b) { u32x4 w; w.x = cvt_pk_bf16(a[0], a[1]); w.y = cvt_pk_bf16(a[2], a[3]); w.z = cvt_pk_bf16(b[0], b[1]); w.w = cvt_pk_bf16(b[2], b[3]); return w; }
;     __device__ __forceinline__ void operator()(const f32x4 (&acc)[2][2][4][2], const Unit& u, int wr, int wc, int fr, int fq) const {
;     ...
;             for (int ai = 0; ai < 2; ++ai) { u32x4 xw[4][2];
; #pragma unroll
;                 for (int m = 0; m < 4; ++m)
; #pragma unroll
;                     for (int bj = 0; bj < 2; ++bj) xw[m][bj] = *(const u32x4*)((const bf16_t*)xin + (size_t)(row0 + ai * HALF + m * 16) * 2048 + col0 + bj * HALF);
; #pragma unroll
;                 for (int m = 0; m < 4; ++m)
; #pragma unroll
;                     for (int bj = 0; bj < 2; ++bj) { const u32x4 w = xw[m][bj];
;                         const f32x4 x0 = (f32x4){__builtin_bit_cast(float, w.x << 16), __builtin_bit_cast(float, w.x & 0xffff0000u), __builtin_bit_cast(float, w.y << 16), __builtin_bit_cast(float, w.y & 0xffff0000u)};
;                         const f32x4 x1 = (f32x4){__builtin_bit_cast(float, w.z << 16), __builtin_bit_cast(float, w.z & 0xffff0000u), __builtin_bit_cast(float, w.w << 16), __builtin_bit_cast(float, w.w & 0xffff0000u)};
;                         *(u32x4*)(xout + (size_t)(row0 + ai * HALF + m * 16) * 2048 + col0 + bj * HALF) = pack8(x0 + gv[bj][0] * acc[ai][bj][m][0], x1 + gv[bj][1] * acc[ai][bj][m][1]); }
;                 asm volatile("" ::: "memory"); }
	v_lshl_add_u64 v[110:111], v[110:111], 0, v[180:181]
	v_cvt_pk_bf16_f32 v107, v112, v113
	v_cvt_pk_bf16_f32 v108, v108, v109
	v_cvt_pk_bf16_f32 v109, v114, v115
	global_store_dwordx4 v[110:111], v[106:109], off
	v_lshlrev_b32_e32 v112, 16, v156
	v_and_b32_e32 v113, 0xffff0000, v156
	v_lshlrev_b32_e32 v106, 16, v154
	v_and_b32_e32 v107, 0xffff0000, v154
	v_lshlrev_b32_e32 v108, 16, v155
	v_and_b32_e32 v109, 0xffff0000, v155
	v_lshlrev_b32_e32 v114, 16, v157
	v_and_b32_e32 v115, 0xffff0000, v157
	v_pk_fma_f32 v[104:105], v[104:105], v[84:85], v[108:109]
	v_pk_fma_f32 v[102:103], v[102:103], v[82:83], v[106:107]
	v_pk_fma_f32 v[106:107], v[100:101], v[76:77], v[114:115]
	v_pk_fma_f32 v[100:101], v[98:99], v[74:75], v[112:113]
	v_cvt_pk_bf16_f32 v98, v102, v103
	v_cvt_pk_bf16_f32 v99, v104, v105
	v_lshlrev_b32_e32 v102, 16, v152
	v_cvt_pk_bf16_f32 v100, v100, v101
	v_cvt_pk_bf16_f32 v101, v106, v107
	global_store_dwordx4 v[110:111], v[98:101], off offset:256
	v_and_b32_e32 v103, 0xffff0000, v152
	v_lshlrev_b32_e32 v104, 16, v153
	v_lshlrev_b32_e32 v98, 16, v150
	v_and_b32_e32 v99, 0xffff0000, v150
	v_and_b32_e32 v105, 0xffff0000, v153
	v_pk_fma_f32 v[86:87], v[86:87], v[94:95], v[98:99]
	v_lshlrev_b32_e32 v100, 16, v151
	v_and_b32_e32 v101, 0xffff0000, v151
	v_pk_fma_f32 v[98:99], v[80:81], v[92:93], v[104:105]
	v_pk_fma_f32 v[80:81], v[78:79], v[90:91], v[102:103]
	v_cvt_pk_bf16_f32 v78, v86, v87
	v_lshl_add_u64 v[86:87], s[60:61], 0, v[186:187]
	v_pk_fma_f32 v[88:89], v[88:89], v[96:97], v[100:101]
	v_lshl_add_u64 v[86:87], v[86:87], 0, v[180:181]
	v_cvt_pk_bf16_f32 v79, v88, v89
	v_cvt_pk_bf16_f32 v80, v80, v81
	v_cvt_pk_bf16_f32 v81, v98, v99
	global_store_dwordx4 v[86:87], v[78:81], off
	v_lshlrev_b32_e32 v88, 16, v140
	v_and_b32_e32 v89, 0xffff0000, v140
	v_lshlrev_b32_e32 v78, 16, v138
	v_and_b32_e32 v79, 0xffff0000, v138
	v_lshlrev_b32_e32 v98, 16, v141
	v_and_b32_e32 v99, 0xffff0000, v141
	v_lshlrev_b32_e32 v80, 16, v139
	v_and_b32_e32 v81, 0xffff0000, v139
	v_pk_fma_f32 v[70:71], v[70:71], v[82:83], v[78:79]
	v_pk_fma_f32 v[78:79], v[68:69], v[76:77], v[98:99]
	v_pk_fma_f32 v[68:69], v[66:67], v[74:75], v[88:89]
	v_pk_fma_f32 v[72:73], v[72:73], v[84:85], v[80:81]
	v_cvt_pk_bf16_f32 v66, v70, v71
	v_lshl_add_u64 v[80:81], v[184:185], 0, s[30:31]
	v_cvt_pk_bf16_f32 v67, v72, v73
	v_cvt_pk_bf16_f32 v68, v68, v69
	v_cvt_pk_bf16_f32 v69, v78, v79
	global_store_dwordx4 v[86:87], v[66:69], off offset:256
	v_lshl_add_u64 v[118:119], v[184:185], 0, s[0:1]
	s_mov_b64 s[0:1], 0xa0000
	v_lshl_add_u64 v[66:67], v[182:183], 0, v[80:81]
	global_load_dwordx4 v[86:89], v[66:67], off
	global_load_dwordx4 v[98:101], v[66:67], off offset:256
	v_lshl_add_u64 v[66:67], v[182:183], 0, v[118:119]
	global_load_dwordx4 v[102:105], v[66:67], off
	global_load_dwordx4 v[106:109], v[66:67], off offset:256
	v_lshl_add_u64 v[120:121], v[184:185], 0, s[0:1]
	v_lshl_add_u64 v[66:67], v[182:183], 0, v[120:121]
	global_load_dwordx4 v[110:113], v[66:67], off
	global_load_dwordx4 v[114:117], v[66:67], off offset:256
	s_mov_b64 s[0:1], 0xb0000
	v_lshl_add_u64 v[78:79], v[184:185], 0, s[0:1]
	v_lshl_add_u64 v[66:67], v[182:183], 0, v[78:79]
	global_load_dwordx4 v[70:73], v[66:67], off
	s_nop 0
	global_load_dwordx4 v[66:69], v[66:67], off offset:256
	s_waitcnt vmcnt(7)
	v_lshlrev_b32_e32 v122, 16, v86
	v_and_b32_e32 v123, 0xffff0000, v86
	v_lshlrev_b32_e32 v86, 16, v87
	v_and_b32_e32 v87, 0xffff0000, v87
	v_lshlrev_b32_e32 v124, 16, v88
	v_and_b32_e32 v125, 0xffff0000, v88
	v_lshlrev_b32_e32 v88, 16, v89
	v_and_b32_e32 v89, 0xffff0000, v89
	v_pk_fma_f32 v[62:63], v[62:63], v[94:95], v[122:123]
	v_pk_fma_f32 v[64:65], v[64:65], v[96:97], v[86:87]
	v_pk_fma_f32 v[86:87], v[60:61], v[92:93], v[88:89]
	v_pk_fma_f32 v[60:61], v[58:59], v[90:91], v[124:125]
	v_cvt_pk_bf16_f32 v58, v62, v63
	v_lshl_add_u64 v[62:63], s[60:61], 0, v[80:81]
	v_cvt_pk_bf16_f32 v59, v64, v65
	v_cvt_pk_bf16_f32 v60, v60, v61
	v_cvt_pk_bf16_f32 v61, v86, v87
	v_lshl_add_u64 v[62:63], v[62:63], 0, v[180:181]
	global_store_dwordx4 v[62:63], v[58:61], off
	s_waitcnt vmcnt(7)
	v_lshlrev_b32_e32 v64, 16, v100
	v_and_b32_e32 v65, 0xffff0000, v100
	v_lshlrev_b32_e32 v58, 16, v98
	v_and_b32_e32 v59, 0xffff0000, v98
	v_lshlrev_b32_e32 v60, 16, v99
	v_and_b32_e32 v61, 0xffff0000, v99
	v_lshlrev_b32_e32 v80, 16, v101
	v_and_b32_e32 v81, 0xffff0000, v101
	v_pk_fma_f32 v[56:57], v[56:57], v[84:85], v[60:61]
	v_pk_fma_f32 v[54:55], v[54:55], v[82:83], v[58:59]
	v_pk_fma_f32 v[58:59], v[52:53], v[76:77], v[80:81]
	v_pk_fma_f32 v[52:53], v[50:51], v[74:75], v[64:65]
	v_cvt_pk_bf16_f32 v50, v54, v55
	v_cvt_pk_bf16_f32 v51, v56, v57
	s_waitcnt vmcnt(6)
; __device__ __forceinline__ u32x4 pack8(const f32x4& a, const f32x4& b) { u32x4 w; w.x = cvt_pk_bf16(a[0], a[1]); w.y = cvt_pk_bf16(a[2], a[3]); w.z = cvt_pk_bf16(b[0], b[1]); w.w = cvt_pk_bf16(b[2], b[3]); return w; }
;     __device__ __forceinline__ void operator()(const f32x4 (&acc)[2][2][4][2], const Unit& u, int wr, int wc, int fr, int fq) const {
;     ...
;                 for (int m = 0; m < 4; ++m)
; #pragma unroll
;                     for (int bj = 0; bj < 2; ++bj) { const u32x4 w = xw[m][bj];
;                         const f32x4 x0 = (f32x4){__builtin_bit_cast(float, w.x << 16), __builtin_bit_cast(float, w.x & 0xffff0000u), __builtin_bit_cast(float, w.y << 16), __builtin_bit_cast(float, w.y & 0xffff0000u)};
;                         const f32x4 x1 = (f32x4){__builtin_bit_cast(float, w.z << 16), __builtin_bit_cast(float, w.z & 0xffff0000u), __builtin_bit_cast(float, w.w << 16), __builtin_bit_cast(float, w.w & 0xffff0000u)};
;                         *(u32x4*)(xout + (size_t)(row0 + ai * HALF + m * 16) * 2048 + col0 + bj * HALF) = pack8(x0 + gv[bj][0] * acc[ai][bj][m][0], x1 + gv[bj][1] * acc[ai][bj][m][1]); }
;                 asm volatile("" ::: "memory"); }
	v_lshlrev_b32_e32 v54, 16, v104
	v_cvt_pk_bf16_f32 v52, v52, v53
	v_cvt_pk_bf16_f32 v53, v58, v59
	global_store_dwordx4 v[62:63], v[50:53], off offset:256
	v_and_b32_e32 v55, 0xffff0000, v104
	v_lshlrev_b32_e32 v56, 16, v105
	v_lshlrev_b32_e32 v50, 16, v102
	v_and_b32_e32 v51, 0xffff0000, v102
	v_and_b32_e32 v57, 0xffff0000, v105
	v_pk_fma_f32 v[46:47], v[46:47], v[94:95], v[50:51]
	v_lshlrev_b32_e32 v52, 16, v103
	v_and_b32_e32 v53, 0xffff0000, v103
	v_pk_fma_f32 v[50:51], v[44:45], v[92:93], v[56:57]
	v_pk_fma_f32 v[44:45], v[42:43], v[90:91], v[54:55]
	v_cvt_pk_bf16_f32 v42, v46, v47
	v_lshl_add_u64 v[46:47], s[60:61], 0, v[118:119]
	v_pk_fma_f32 v[48:49], v[48:49], v[96:97], v[52:53]
	v_lshl_add_u64 v[46:47], v[46:47], 0, v[180:181]
	v_cvt_pk_bf16_f32 v43, v48, v49
	v_cvt_pk_bf16_f32 v44, v44, v45
	v_cvt_pk_bf16_f32 v45, v50, v51
	global_store_dwordx4 v[46:47], v[42:45], off
	s_waitcnt vmcnt(7)
	v_lshlrev_b32_e32 v48, 16, v108
	v_and_b32_e32 v49, 0xffff0000, v108
	v_lshlrev_b32_e32 v42, 16, v106
	v_and_b32_e32 v43, 0xffff0000, v106
	v_lshlrev_b32_e32 v44, 16, v107
	v_and_b32_e32 v45, 0xffff0000, v107
	v_lshlrev_b32_e32 v50, 16, v109
	v_and_b32_e32 v51, 0xffff0000, v109
	v_pk_fma_f32 v[40:41], v[40:41], v[84:85], v[44:45]
	v_pk_fma_f32 v[38:39], v[38:39], v[82:83], v[42:43]
	v_pk_fma_f32 v[42:43], v[36:37], v[76:77], v[50:51]
	v_pk_fma_f32 v[36:37], v[34:35], v[74:75], v[48:49]
	v_cvt_pk_bf16_f32 v34, v38, v39
	v_cvt_pk_bf16_f32 v35, v40, v41
	s_waitcnt vmcnt(6)
	v_lshlrev_b32_e32 v38, 16, v112
	v_cvt_pk_bf16_f32 v36, v36, v37
	v_cvt_pk_bf16_f32 v37, v42, v43
	global_store_dwordx4 v[46:47], v[34:37], off offset:256
	v_and_b32_e32 v39, 0xffff0000, v112
	v_lshlrev_b32_e32 v40, 16, v113
	v_lshlrev_b32_e32 v34, 16, v110
	v_and_b32_e32 v35, 0xffff0000, v110
	v_and_b32_e32 v41, 0xffff0000, v113
	v_pk_fma_f32 v[30:31], v[30:31], v[94:95], v[34:35]
	v_lshlrev_b32_e32 v36, 16, v111
	v_and_b32_e32 v37, 0xffff0000, v111
	v_pk_fma_f32 v[34:35], v[28:29], v[92:93], v[40:41]
	v_pk_fma_f32 v[28:29], v[26:27], v[90:91], v[38:39]
	v_cvt_pk_bf16_f32 v26, v30, v31
	v_lshl_add_u64 v[30:31], s[60:61], 0, v[120:121]
	v_pk_fma_f32 v[32:33], v[32:33], v[96:97], v[36:37]
	v_lshl_add_u64 v[30:31], v[30:31], 0, v[180:181]
	v_cvt_pk_bf16_f32 v27, v32, v33
	v_cvt_pk_bf16_f32 v28, v28, v29
	v_cvt_pk_bf16_f32 v29, v34, v35
	global_store_dwordx4 v[30:31], v[26:29], off
	s_waitcnt vmcnt(7)
	v_lshlrev_b32_e32 v32, 16, v116
	v_and_b32_e32 v33, 0xffff0000, v116
	v_lshlrev_b32_e32 v26, 16, v114
	v_and_b32_e32 v27, 0xffff0000, v114
	v_lshlrev_b32_e32 v28, 16, v115
	v_and_b32_e32 v29, 0xffff0000, v115
	v_lshlrev_b32_e32 v34, 16, v117
	v_and_b32_e32 v35, 0xffff0000, v117
	v_pk_fma_f32 v[24:25], v[24:25], v[84:85], v[28:29]
	v_pk_fma_f32 v[22:23], v[22:23], v[82:83], v[26:27]
	v_pk_fma_f32 v[26:27], v[20:21], v[76:77], v[34:35]
	v_pk_fma_f32 v[20:21], v[18:19], v[74:75], v[32:33]
	v_cvt_pk_bf16_f32 v18, v22, v23
	v_cvt_pk_bf16_f32 v19, v24, v25
	s_waitcnt vmcnt(6)
	v_lshlrev_b32_e32 v22, 16, v72
	v_cvt_pk_bf16_f32 v20, v20, v21
	v_cvt_pk_bf16_f32 v21, v26, v27
	global_store_dwordx4 v[30:31], v[18:21], off offset:256
	v_and_b32_e32 v23, 0xffff0000, v72
	v_lshlrev_b32_e32 v24, 16, v73
	v_lshlrev_b32_e32 v18, 16, v70
	v_and_b32_e32 v19, 0xffff0000, v70
	v_and_b32_e32 v25, 0xffff0000, v73
	v_pk_fma_f32 v[14:15], v[14:15], v[94:95], v[18:19]
	v_lshlrev_b32_e32 v20, 16, v71
	v_and_b32_e32 v21, 0xffff0000, v71
	v_pk_fma_f32 v[18:19], v[12:13], v[92:93], v[24:25]
	v_pk_fma_f32 v[12:13], v[10:11], v[90:91], v[22:23]
	v_cvt_pk_bf16_f32 v10, v14, v15
	v_lshl_add_u64 v[14:15], s[60:61], 0, v[78:79]
	v_pk_fma_f32 v[16:17], v[16:17], v[96:97], v[20:21]
	v_lshl_add_u64 v[14:15], v[14:15], 0, v[180:181]
	v_cvt_pk_bf16_f32 v11, v16, v17
	v_cvt_pk_bf16_f32 v12, v12, v13
	v_cvt_pk_bf16_f32 v13, v18, v19
	global_store_dwordx4 v[14:15], v[10:13], off
	s_waitcnt vmcnt(7)
	v_lshlrev_b32_e32 v16, 16, v68
	v_and_b32_e32 v17, 0xffff0000, v68
	v_lshlrev_b32_e32 v10, 16, v66
	v_and_b32_e32 v11, 0xffff0000, v66
	v_lshlrev_b32_e32 v18, 16, v69
	v_and_b32_e32 v19, 0xffff0000, v69
	v_lshlrev_b32_e32 v12, 16, v67
	v_and_b32_e32 v13, 0xffff0000, v67
	v_pk_fma_f32 v[6:7], v[6:7], v[82:83], v[10:11]
	v_pk_fma_f32 v[10:11], v[4:5], v[76:77], v[18:19]
	v_pk_fma_f32 v[4:5], v[2:3], v[74:75], v[16:17]
	v_pk_fma_f32 v[8:9], v[8:9], v[84:85], v[12:13]
	v_cvt_pk_bf16_f32 v2, v6, v7
	s_nop 0
	v_cvt_pk_bf16_f32 v3, v8, v9
	v_cvt_pk_bf16_f32 v4, v4, v5
	v_cvt_pk_bf16_f32 v5, v10, v11
	global_store_dwordx4 v[14:15], v[2:5], off offset:256
	s_cbranch_vccnz .LBB0_2089
	s_and_b64 vcc, exec, s[6:7]
	s_cbranch_vccnz .LBB0_2088
	s_barrier
	s_branch .LBB0_2088

; __device__ __forceinline__ u32x4 pack8(const f32x4& a, const f32x4& b) { u32x4 w; w.x = cvt_pk_bf16(a[0], a[1]); w.y = cvt_pk_bf16(a[2], a[3]); w.z = cvt_pk_bf16(b[0], b[1]); w.w = cvt_pk_bf16(b[2], b[3]); return w; }
;     __device__ __forceinline__ void operator()(const f32x4 (&acc)[2][2][4][2], const Unit& u, int wr, int wc, int fr, int fq) const {
;         const int row0 = u.pm * BM + wr * 64 + fr, col0 = u.pn * BM + wc * 32 + 8 * fq;
;         const float* gp = gate + (size_t)(u.pm >> 3) * 12288 + col0;
;         f32x4 gv[2][2];
; #pragma unroll
;         for (int bj = 0; bj < 2; ++bj)
; #pragma unroll
;             for (int n = 0; n < 2; ++n) { gv[bj][n] = *(const f32x4*)(gp + bj * HALF + n * 4); if (cscale) gv[bj][n] = gv[bj][n] * *(const f32x4*)(cscale + col0 + bj * HALF + n * 4); }
;     ...
;             for (int ai = 0; ai < 2; ++ai) { u32x4 xw[4][2];
; #pragma unroll
;                 for (int m = 0; m < 4; ++m)
; #pragma unroll
;                     for (int bj = 0; bj < 2; ++bj) xw[m][bj] = *(const u32x4*)((const bf16_t*)xin + (size_t)(row0 + ai * HALF + m * 16) * 2048 + col0 + bj * HALF);
; #pragma unroll
;                 for (int m = 0; m < 4; ++m)
; #pragma unroll
;                     for (int bj = 0; bj < 2; ++bj) { const u32x4 w = xw[m][bj];
;                         const f32x4 x0 = (f32x4){__builtin_bit_cast(float, w.x << 16), __builtin_bit_cast(float, w.x & 0xffff0000u), __builtin_bit_cast(float, w.y << 16), __builtin_bit_cast(float, w.y & 0xffff0000u)};
;                         const f32x4 x1 = (f32x4){__builtin_bit_cast(float, w.z << 16), __builtin_bit_cast(float, w.z & 0xffff0000u), __builtin_bit_cast(float, w.w << 16), __builtin_bit_cast(float, w.w & 0xffff0000u)};
;                         *(u32x4*)(xout + (size_t)(row0 + ai * HALF + m * 16) * 2048 + col0 + bj * HALF) = pack8(x0 + gv[bj][0] * acc[ai][bj][m][0], x1 + gv[bj][1] * acc[ai][bj][m][1]); }
.LBB0_2393:
	v_mov_b32_e32 v84, v252
	s_lshl_b32 s0, s82, 8
	v_ashrrev_i32_e32 v82, 1, v84
	s_or_b32 s0, s0, s72
	v_and_b32_e32 v82, -8, v82
	v_add_u32_e32 v82, s0, v82
	s_ashr_i32 s0, s81, 3
	s_mul_hi_i32 s1, s0, 0xc000
	s_mul_i32 s0, s0, 0xc000
	s_add_u32 s0, s55, s0
	s_addc_u32 s1, s70, s1
	s_lshl_b32 s33, s81, 8
	s_add_i32 s33, s33, s71
	v_ashrrev_i32_e32 v83, 31, v82
	v_and_or_b32 v146, v84, 15, s33
	v_lshlrev_b64 v[180:181], 1, v[82:83]
	v_ashrrev_i32_e32 v147, 31, v146
	v_lshl_add_u64 v[182:183], s[60:61], 0, v[180:181]
	v_lshlrev_b64 v[184:185], 12, v[146:147]
	v_or_b32_e32 v148, 16, v146
	v_lshl_add_u64 v[84:85], v[182:183], 0, v[184:185]
	v_ashrrev_i32_e32 v149, 31, v148
	global_load_dwordx4 v[196:199], v[84:85], off
	global_load_dwordx4 v[200:203], v[84:85], off offset:256
	v_lshl_add_u64 v[86:87], v[82:83], 2, s[0:1]
	v_lshlrev_b64 v[190:191], 12, v[148:149]
	global_load_dwordx4 v[102:105], v[86:87], off
	global_load_dwordx4 v[98:101], v[86:87], off offset:16
	global_load_dwordx4 v[82:85], v[86:87], off offset:528
	s_nop 0
	global_load_dwordx4 v[86:89], v[86:87], off offset:512
	v_lshl_add_u64 v[148:149], v[182:183], 0, v[190:191]
	global_load_dwordx4 v[166:169], v[148:149], off
	global_load_dwordx4 v[154:157], v[148:149], off offset:256
	v_or_b32_e32 v148, 32, v146
	v_ashrrev_i32_e32 v149, 31, v148
	v_lshlrev_b64 v[188:189], 12, v[148:149]
	v_lshl_add_u64 v[148:149], v[182:183], 0, v[188:189]
	global_load_dwordx4 v[150:153], v[148:149], off
	v_or_b32_e32 v146, 48, v146
	v_ashrrev_i32_e32 v147, 31, v146
	v_lshlrev_b64 v[186:187], 12, v[146:147]
	v_lshl_add_u64 v[146:147], s[60:61], 0, v[184:185]
	v_lshl_add_u64 v[204:205], v[182:183], 0, v[186:187]
	v_lshl_add_u64 v[206:207], v[146:147], 0, v[180:181]
	global_load_dwordx4 v[162:165], v[148:149], off offset:256
	global_load_dwordx4 v[158:161], v[204:205], off
	s_nop 0
	global_load_dwordx4 v[146:149], v[204:205], off offset:256
	s_mov_b64 s[0:1], 0x80000
	s_and_b64 vcc, exec, s[8:9]
	s_mov_b64 s[8:9], -1
	s_waitcnt vmcnt(0)
	v_lshlrev_b32_e32 v204, 16, v196
	v_and_b32_e32 v205, 0xffff0000, v196
	v_lshlrev_b32_e32 v196, 16, v197
	v_and_b32_e32 v197, 0xffff0000, v197
	v_lshlrev_b32_e32 v208, 16, v198
	v_and_b32_e32 v209, 0xffff0000, v198
	v_lshlrev_b32_e32 v198, 16, v199
	v_and_b32_e32 v199, 0xffff0000, v199
	v_lshlrev_b32_e32 v210, 16, v200
	v_and_b32_e32 v211, 0xffff0000, v200
	v_lshlrev_b32_e32 v200, 16, v201
	v_and_b32_e32 v201, 0xffff0000, v201
	v_lshlrev_b32_e32 v212, 16, v202
	v_and_b32_e32 v213, 0xffff0000, v202
	v_lshlrev_b32_e32 v202, 16, v203
	v_and_b32_e32 v203, 0xffff0000, v203
	v_pk_fma_f32 v[144:145], v[144:145], v[104:105], v[196:197]
	v_pk_fma_f32 v[140:141], v[140:141], v[100:101], v[198:199]
	v_pk_fma_f32 v[136:137], v[136:137], v[88:89], v[200:201]
	v_pk_fma_f32 v[196:197], v[132:133], v[84:85], v[202:203]
	v_lshlrev_b32_e32 v200, 16, v166
	v_and_b32_e32 v201, 0xffff0000, v166
	v_lshlrev_b32_e32 v202, 16, v168
	v_and_b32_e32 v203, 0xffff0000, v168
	v_pk_fma_f32 v[142:143], v[142:143], v[102:103], v[204:205]
	v_pk_fma_f32 v[138:139], v[138:139], v[98:99], v[208:209]
	v_pk_fma_f32 v[134:135], v[134:135], v[86:87], v[210:211]
	v_pk_fma_f32 v[198:199], v[130:131], v[82:83], v[212:213]
	v_lshlrev_b32_e32 v168, 16, v169
	v_and_b32_e32 v169, 0xffff0000, v169
	v_cvt_pk_bf16_f32 v130, v142, v143
	v_cvt_pk_bf16_f32 v131, v144, v145
	v_cvt_pk_bf16_f32 v132, v138, v139
	v_cvt_pk_bf16_f32 v133, v140, v141
	v_pk_fma_f32 v[126:127], v[126:127], v[102:103], v[200:201]
	v_pk_fma_f32 v[140:141], v[122:123], v[98:99], v[202:203]
	global_store_dwordx4 v[206:207], v[130:133], off
	v_cvt_pk_bf16_f32 v122, v134, v135
	v_lshlrev_b32_e32 v166, 16, v167
	v_and_b32_e32 v167, 0xffff0000, v167
	v_pk_fma_f32 v[138:139], v[124:125], v[100:101], v[168:169]
	v_cvt_pk_bf16_f32 v123, v136, v137
	v_cvt_pk_bf16_f32 v124, v198, v199
	v_cvt_pk_bf16_f32 v125, v196, v197
	global_store_dwordx4 v[206:207], v[122:125], off offset:256
	v_pk_fma_f32 v[128:129], v[128:129], v[104:105], v[166:167]
	v_lshlrev_b32_e32 v130, 16, v157
	v_cvt_pk_bf16_f32 v122, v126, v127
	v_lshl_add_u64 v[126:127], s[60:61], 0, v[190:191]
	v_cvt_pk_bf16_f32 v123, v128, v129
	v_cvt_pk_bf16_f32 v124, v140, v141
	v_cvt_pk_bf16_f32 v125, v138, v139
	v_lshl_add_u64 v[126:127], v[126:127], 0, v[180:181]
	global_store_dwordx4 v[126:127], v[122:125], off
	v_lshlrev_b32_e32 v128, 16, v156
	v_and_b32_e32 v129, 0xffff0000, v156
	v_lshlrev_b32_e32 v122, 16, v154
	v_and_b32_e32 v123, 0xffff0000, v154
	v_lshlrev_b32_e32 v124, 16, v155
	v_and_b32_e32 v125, 0xffff0000, v155
	v_and_b32_e32 v131, 0xffff0000, v157
	v_pk_fma_f32 v[120:121], v[120:121], v[88:89], v[124:125]
	v_pk_fma_f32 v[118:119], v[118:119], v[86:87], v[122:123]
	v_pk_fma_f32 v[122:123], v[116:117], v[84:85], v[130:131]
	v_pk_fma_f32 v[116:117], v[114:115], v[82:83], v[128:129]
	v_cvt_pk_bf16_f32 v114, v118, v119
	v_cvt_pk_bf16_f32 v115, v120, v121
	v_lshlrev_b32_e32 v118, 16, v152
	v_cvt_pk_bf16_f32 v116, v116, v117
	v_cvt_pk_bf16_f32 v117, v122, v123
	global_store_dwordx4 v[126:127], v[114:117], off offset:256
	v_and_b32_e32 v119, 0xffff0000, v152
	v_lshlrev_b32_e32 v120, 16, v153
	v_lshlrev_b32_e32 v114, 16, v150
	v_and_b32_e32 v115, 0xffff0000, v150
	v_and_b32_e32 v121, 0xffff0000, v153
	v_pk_fma_f32 v[110:111], v[110:111], v[102:103], v[114:115]
	v_lshlrev_b32_e32 v116, 16, v151
	v_and_b32_e32 v117, 0xffff0000, v151
	v_pk_fma_f32 v[114:115], v[108:109], v[100:101], v[120:121]
	v_pk_fma_f32 v[108:109], v[106:107], v[98:99], v[118:119]
	v_cvt_pk_bf16_f32 v106, v110, v111
	v_lshl_add_u64 v[110:111], s[60:61], 0, v[188:189]
	v_pk_fma_f32 v[112:113], v[112:113], v[104:105], v[116:117]
; __device__ __forceinline__ u32x4 pack8(const f32x4& a, const f32x4& b) { u32x4 w; w.x = cvt_pk_bf16(a[0], a[1]); w.y = cvt_pk_bf16(a[2], a[3]); w.z = cvt_pk_bf16(b[0], b[1]); w.w = cvt_pk_bf16(b[2], b[3]); return w; }
;     __device__ __forceinline__ void operator()(const f32x4 (&acc)[2][2][4][2], const Unit& u, int wr, int wc, int fr, int fq) const {
;     ...
;             for (int ai = 0; ai < 2; ++ai) { u32x4 xw[4][2];
; #pragma unroll
;                 for (int m = 0; m < 4; ++m)
; #pragma unroll
;                     for (int bj = 0; bj < 2; ++bj) xw[m][bj] = *(const u32x4*)((const bf16_t*)xin + (size_t)(row0 + ai * HALF + m * 16) * 2048 + col0 + bj * HALF);
; #pragma unroll
;                 for (int m = 0; m < 4; ++m)
; #pragma unroll
;                     for (int bj = 0; bj < 2; ++bj) { const u32x4 w = xw[m][bj];
;                         const f32x4 x0 = (f32x4){__builtin_bit_cast(float, w.x << 16), __builtin_bit_cast(float, w.x & 0xffff0000u), __builtin_bit_cast(float, w.y << 16), __builtin_bit_cast(float, w.y & 0xffff0000u)};
;                         const f32x4 x1 = (f32x4){__builtin_bit_cast(float, w.z << 16), __builtin_bit_cast(float, w.z & 0xffff0000u), __builtin_bit_cast(float, w.w << 16), __builtin_bit_cast(float, w.w & 0xffff0000u)};
;                         *(u32x4*)(xout + (size_t)(row0 + ai * HALF + m * 16) * 2048 + col0 + bj * HALF) = pack8(x0 + gv[bj][0] * acc[ai][bj][m][0], x1 + gv[bj][1] * acc[ai][bj][m][1]); }
;                 asm volatile("" ::: "memory"); }
	v_lshl_add_u64 v[110:111], v[110:111], 0, v[180:181]
	v_cvt_pk_bf16_f32 v107, v112, v113
	v_cvt_pk_bf16_f32 v108, v108, v109
	v_cvt_pk_bf16_f32 v109, v114, v115
	global_store_dwordx4 v[110:111], v[106:109], off
	v_lshlrev_b32_e32 v112, 16, v164
	v_and_b32_e32 v113, 0xffff0000, v164
	v_lshlrev_b32_e32 v106, 16, v162
	v_and_b32_e32 v107, 0xffff0000, v162
	v_lshlrev_b32_e32 v108, 16, v163
	v_and_b32_e32 v109, 0xffff0000, v163
	v_lshlrev_b32_e32 v114, 16, v165
	v_and_b32_e32 v115, 0xffff0000, v165
	v_pk_fma_f32 v[96:97], v[96:97], v[88:89], v[108:109]
	v_pk_fma_f32 v[94:95], v[94:95], v[86:87], v[106:107]
	v_pk_fma_f32 v[106:107], v[92:93], v[84:85], v[114:115]
	v_pk_fma_f32 v[92:93], v[90:91], v[82:83], v[112:113]
	v_cvt_pk_bf16_f32 v90, v94, v95
	v_cvt_pk_bf16_f32 v91, v96, v97
	v_lshlrev_b32_e32 v94, 16, v160
	v_cvt_pk_bf16_f32 v92, v92, v93
	v_cvt_pk_bf16_f32 v93, v106, v107
	global_store_dwordx4 v[110:111], v[90:93], off offset:256
	v_and_b32_e32 v95, 0xffff0000, v160
	v_lshlrev_b32_e32 v96, 16, v161
	v_lshlrev_b32_e32 v90, 16, v158
	v_and_b32_e32 v91, 0xffff0000, v158
	v_and_b32_e32 v97, 0xffff0000, v161
	v_pk_fma_f32 v[78:79], v[78:79], v[102:103], v[90:91]
	v_lshlrev_b32_e32 v92, 16, v159
	v_and_b32_e32 v93, 0xffff0000, v159
	v_pk_fma_f32 v[90:91], v[76:77], v[100:101], v[96:97]
	v_pk_fma_f32 v[76:77], v[74:75], v[98:99], v[94:95]
	v_cvt_pk_bf16_f32 v74, v78, v79
	v_lshl_add_u64 v[78:79], s[60:61], 0, v[186:187]
	v_pk_fma_f32 v[80:81], v[80:81], v[104:105], v[92:93]
	v_lshl_add_u64 v[78:79], v[78:79], 0, v[180:181]
	v_cvt_pk_bf16_f32 v75, v80, v81
	v_cvt_pk_bf16_f32 v76, v76, v77
	v_cvt_pk_bf16_f32 v77, v90, v91
	global_store_dwordx4 v[78:79], v[74:77], off
	v_lshlrev_b32_e32 v80, 16, v148
	v_and_b32_e32 v81, 0xffff0000, v148
	v_lshlrev_b32_e32 v74, 16, v146
	v_and_b32_e32 v75, 0xffff0000, v146
	v_lshlrev_b32_e32 v90, 16, v149
	v_and_b32_e32 v91, 0xffff0000, v149
	v_lshlrev_b32_e32 v76, 16, v147
	v_and_b32_e32 v77, 0xffff0000, v147
	v_pk_fma_f32 v[70:71], v[70:71], v[86:87], v[74:75]
	v_pk_fma_f32 v[74:75], v[68:69], v[84:85], v[90:91]
	v_pk_fma_f32 v[68:69], v[66:67], v[82:83], v[80:81]
	v_pk_fma_f32 v[72:73], v[72:73], v[88:89], v[76:77]
	v_cvt_pk_bf16_f32 v66, v70, v71
	v_lshl_add_u64 v[80:81], v[184:185], 0, s[0:1]
	v_cvt_pk_bf16_f32 v67, v72, v73
	v_cvt_pk_bf16_f32 v68, v68, v69
	v_cvt_pk_bf16_f32 v69, v74, v75
	global_store_dwordx4 v[78:79], v[66:69], off offset:256
	s_mov_b64 s[0:1], 0x90000
	v_lshl_add_u64 v[118:119], v[184:185], 0, s[0:1]
	v_lshl_add_u64 v[66:67], v[182:183], 0, v[80:81]
	global_load_dwordx4 v[76:79], v[66:67], off
	global_load_dwordx4 v[90:93], v[66:67], off offset:256
	v_lshl_add_u64 v[66:67], v[182:183], 0, v[118:119]
	global_load_dwordx4 v[94:97], v[66:67], off
	global_load_dwordx4 v[106:109], v[66:67], off offset:256
	s_mov_b64 s[0:1], 0xa0000
	v_lshl_add_u64 v[120:121], v[184:185], 0, s[0:1]
	v_lshl_add_u64 v[66:67], v[182:183], 0, v[120:121]
	global_load_dwordx4 v[110:113], v[66:67], off
	global_load_dwordx4 v[114:117], v[66:67], off offset:256
	v_lshl_add_u64 v[74:75], v[184:185], 0, s[30:31]
	v_lshl_add_u64 v[66:67], v[182:183], 0, v[74:75]
	global_load_dwordx4 v[70:73], v[66:67], off
	s_nop 0
	global_load_dwordx4 v[66:69], v[66:67], off offset:256
	s_waitcnt vmcnt(7)
	v_lshlrev_b32_e32 v122, 16, v76
	v_and_b32_e32 v123, 0xffff0000, v76
	v_lshlrev_b32_e32 v76, 16, v77
	v_and_b32_e32 v77, 0xffff0000, v77
	v_lshlrev_b32_e32 v124, 16, v78
	v_and_b32_e32 v125, 0xffff0000, v78
	v_lshlrev_b32_e32 v78, 16, v79
	v_and_b32_e32 v79, 0xffff0000, v79
	v_pk_fma_f32 v[62:63], v[62:63], v[102:103], v[122:123]
	v_pk_fma_f32 v[64:65], v[64:65], v[104:105], v[76:77]
	v_pk_fma_f32 v[76:77], v[60:61], v[100:101], v[78:79]
	v_pk_fma_f32 v[60:61], v[58:59], v[98:99], v[124:125]
	v_cvt_pk_bf16_f32 v58, v62, v63
	v_lshl_add_u64 v[62:63], s[60:61], 0, v[80:81]
	v_cvt_pk_bf16_f32 v59, v64, v65
	v_cvt_pk_bf16_f32 v60, v60, v61
	v_cvt_pk_bf16_f32 v61, v76, v77
	v_lshl_add_u64 v[62:63], v[62:63], 0, v[180:181]
	global_store_dwordx4 v[62:63], v[58:61], off
	s_waitcnt vmcnt(7)
	v_lshlrev_b32_e32 v64, 16, v92
	v_and_b32_e32 v65, 0xffff0000, v92
	v_lshlrev_b32_e32 v58, 16, v90
	v_and_b32_e32 v59, 0xffff0000, v90
	v_lshlrev_b32_e32 v60, 16, v91
	v_and_b32_e32 v61, 0xffff0000, v91
	v_lshlrev_b32_e32 v76, 16, v93
	v_and_b32_e32 v77, 0xffff0000, v93
	v_pk_fma_f32 v[56:57], v[56:57], v[88:89], v[60:61]
	v_pk_fma_f32 v[54:55], v[54:55], v[86:87], v[58:59]
	v_pk_fma_f32 v[58:59], v[52:53], v[84:85], v[76:77]
	v_pk_fma_f32 v[52:53], v[50:51], v[82:83], v[64:65]
	v_cvt_pk_bf16_f32 v50, v54, v55
	v_cvt_pk_bf16_f32 v51, v56, v57
	s_waitcnt vmcnt(6)
; __device__ __forceinline__ u32x4 pack8(const f32x4& a, const f32x4& b) { u32x4 w; w.x = cvt_pk_bf16(a[0], a[1]); w.y = cvt_pk_bf16(a[2], a[3]); w.z = cvt_pk_bf16(b[0], b[1]); w.w = cvt_pk_bf16(b[2], b[3]); return w; }
;     __device__ __forceinline__ void operator()(const f32x4 (&acc)[2][2][4][2], const Unit& u, int wr, int wc, int fr, int fq) const {
;     ...
;                 for (int m = 0; m < 4; ++m)
; #pragma unroll
;                     for (int bj = 0; bj < 2; ++bj) { const u32x4 w = xw[m][bj];
;                         const f32x4 x0 = (f32x4){__builtin_bit_cast(float, w.x << 16), __builtin_bit_cast(float, w.x & 0xffff0000u), __builtin_bit_cast(float, w.y << 16), __builtin_bit_cast(float, w.y & 0xffff0000u)};
;                         const f32x4 x1 = (f32x4){__builtin_bit_cast(float, w.z << 16), __builtin_bit_cast(float, w.z & 0xffff0000u), __builtin_bit_cast(float, w.w << 16), __builtin_bit_cast(float, w.w & 0xffff0000u)};
;                         *(u32x4*)(xout + (size_t)(row0 + ai * HALF + m * 16) * 2048 + col0 + bj * HALF) = pack8(x0 + gv[bj][0] * acc[ai][bj][m][0], x1 + gv[bj][1] * acc[ai][bj][m][1]); }
;                 asm volatile("" ::: "memory"); }
	v_lshlrev_b32_e32 v54, 16, v96
	v_cvt_pk_bf16_f32 v52, v52, v53
	v_cvt_pk_bf16_f32 v53, v58, v59
	global_store_dwordx4 v[62:63], v[50:53], off offset:256
	v_and_b32_e32 v55, 0xffff0000, v96
	v_lshlrev_b32_e32 v56, 16, v97
	v_lshlrev_b32_e32 v50, 16, v94
	v_and_b32_e32 v51, 0xffff0000, v94
	v_and_b32_e32 v57, 0xffff0000, v97
	v_pk_fma_f32 v[46:47], v[46:47], v[102:103], v[50:51]
	v_lshlrev_b32_e32 v52, 16, v95
	v_and_b32_e32 v53, 0xffff0000, v95
	v_pk_fma_f32 v[50:51], v[44:45], v[100:101], v[56:57]
	v_pk_fma_f32 v[44:45], v[42:43], v[98:99], v[54:55]
	v_cvt_pk_bf16_f32 v42, v46, v47
	v_lshl_add_u64 v[46:47], s[60:61], 0, v[118:119]
	v_pk_fma_f32 v[48:49], v[48:49], v[104:105], v[52:53]
	v_lshl_add_u64 v[46:47], v[46:47], 0, v[180:181]
	v_cvt_pk_bf16_f32 v43, v48, v49
	v_cvt_pk_bf16_f32 v44, v44, v45
	v_cvt_pk_bf16_f32 v45, v50, v51
	global_store_dwordx4 v[46:47], v[42:45], off
	s_waitcnt vmcnt(7)
	v_lshlrev_b32_e32 v48, 16, v108
	v_and_b32_e32 v49, 0xffff0000, v108
	v_lshlrev_b32_e32 v42, 16, v106
	v_and_b32_e32 v43, 0xffff0000, v106
	v_lshlrev_b32_e32 v44, 16, v107
	v_and_b32_e32 v45, 0xffff0000, v107
	v_lshlrev_b32_e32 v50, 16, v109
	v_and_b32_e32 v51, 0xffff0000, v109
	v_pk_fma_f32 v[40:41], v[40:41], v[88:89], v[44:45]
	v_pk_fma_f32 v[38:39], v[38:39], v[86:87], v[42:43]
	v_pk_fma_f32 v[42:43], v[36:37], v[84:85], v[50:51]
	v_pk_fma_f32 v[36:37], v[34:35], v[82:83], v[48:49]
	v_cvt_pk_bf16_f32 v34, v38, v39
	v_cvt_pk_bf16_f32 v35, v40, v41
	s_waitcnt vmcnt(6)
	v_lshlrev_b32_e32 v38, 16, v112
	v_cvt_pk_bf16_f32 v36, v36, v37
	v_cvt_pk_bf16_f32 v37, v42, v43
	global_store_dwordx4 v[46:47], v[34:37], off offset:256
	v_and_b32_e32 v39, 0xffff0000, v112
	v_lshlrev_b32_e32 v40, 16, v113
	v_lshlrev_b32_e32 v34, 16, v110
	v_and_b32_e32 v35, 0xffff0000, v110
	v_and_b32_e32 v41, 0xffff0000, v113
	v_pk_fma_f32 v[30:31], v[30:31], v[102:103], v[34:35]
	v_lshlrev_b32_e32 v36, 16, v111
	v_and_b32_e32 v37, 0xffff0000, v111
	v_pk_fma_f32 v[34:35], v[28:29], v[100:101], v[40:41]
	v_pk_fma_f32 v[28:29], v[26:27], v[98:99], v[38:39]
	v_cvt_pk_bf16_f32 v26, v30, v31
	v_lshl_add_u64 v[30:31], s[60:61], 0, v[120:121]
	v_pk_fma_f32 v[32:33], v[32:33], v[104:105], v[36:37]
	v_lshl_add_u64 v[30:31], v[30:31], 0, v[180:181]
	v_cvt_pk_bf16_f32 v27, v32, v33
	v_cvt_pk_bf16_f32 v28, v28, v29
	v_cvt_pk_bf16_f32 v29, v34, v35
	global_store_dwordx4 v[30:31], v[26:29], off
	s_waitcnt vmcnt(7)
	v_lshlrev_b32_e32 v32, 16, v116
	v_and_b32_e32 v33, 0xffff0000, v116
	v_lshlrev_b32_e32 v26, 16, v114
	v_and_b32_e32 v27, 0xffff0000, v114
	v_lshlrev_b32_e32 v28, 16, v115
	v_and_b32_e32 v29, 0xffff0000, v115
	v_lshlrev_b32_e32 v34, 16, v117
	v_and_b32_e32 v35, 0xffff0000, v117
	v_pk_fma_f32 v[24:25], v[24:25], v[88:89], v[28:29]
	v_pk_fma_f32 v[22:23], v[22:23], v[86:87], v[26:27]
	v_pk_fma_f32 v[26:27], v[20:21], v[84:85], v[34:35]
	v_pk_fma_f32 v[20:21], v[18:19], v[82:83], v[32:33]
	v_cvt_pk_bf16_f32 v18, v22, v23
	v_cvt_pk_bf16_f32 v19, v24, v25
	s_waitcnt vmcnt(6)
	v_lshlrev_b32_e32 v22, 16, v72
	v_cvt_pk_bf16_f32 v20, v20, v21
	v_cvt_pk_bf16_f32 v21, v26, v27
	global_store_dwordx4 v[30:31], v[18:21], off offset:256
	v_and_b32_e32 v23, 0xffff0000, v72
	v_lshlrev_b32_e32 v24, 16, v73
	v_lshlrev_b32_e32 v18, 16, v70
	v_and_b32_e32 v19, 0xffff0000, v70
	v_and_b32_e32 v25, 0xffff0000, v73
	v_pk_fma_f32 v[14:15], v[14:15], v[102:103], v[18:19]
	v_lshlrev_b32_e32 v20, 16, v71
	v_and_b32_e32 v21, 0xffff0000, v71
	v_pk_fma_f32 v[18:19], v[12:13], v[100:101], v[24:25]
	v_pk_fma_f32 v[12:13], v[10:11], v[98:99], v[22:23]
	v_cvt_pk_bf16_f32 v10, v14, v15
	v_lshl_add_u64 v[14:15], s[60:61], 0, v[74:75]
	v_pk_fma_f32 v[16:17], v[16:17], v[104:105], v[20:21]
	v_lshl_add_u64 v[14:15], v[14:15], 0, v[180:181]
	v_cvt_pk_bf16_f32 v11, v16, v17
	v_cvt_pk_bf16_f32 v12, v12, v13
	v_cvt_pk_bf16_f32 v13, v18, v19
	global_store_dwordx4 v[14:15], v[10:13], off
	s_waitcnt vmcnt(7)
	v_lshlrev_b32_e32 v16, 16, v68
	v_and_b32_e32 v17, 0xffff0000, v68
	v_lshlrev_b32_e32 v10, 16, v66
	v_and_b32_e32 v11, 0xffff0000, v66
	v_lshlrev_b32_e32 v18, 16, v69
	v_and_b32_e32 v19, 0xffff0000, v69
	v_lshlrev_b32_e32 v12, 16, v67
	v_and_b32_e32 v13, 0xffff0000, v67
	v_pk_fma_f32 v[6:7], v[6:7], v[86:87], v[10:11]
	v_pk_fma_f32 v[10:11], v[4:5], v[84:85], v[18:19]
	v_pk_fma_f32 v[4:5], v[2:3], v[82:83], v[16:17]
	v_pk_fma_f32 v[8:9], v[8:9], v[88:89], v[12:13]
	v_cvt_pk_bf16_f32 v2, v6, v7
	s_nop 0
	v_cvt_pk_bf16_f32 v3, v8, v9
	v_cvt_pk_bf16_f32 v4, v4, v5
	v_cvt_pk_bf16_f32 v5, v10, v11
	global_store_dwordx4 v[14:15], v[2:5], off offset:256
	s_cbranch_vccnz .LBB0_2378
	s_and_b64 vcc, exec, s[6:7]
	s_cbranch_vccnz .LBB0_2377
	s_barrier
	s_branch .LBB0_2377

; __device__ __forceinline__ u32x4 pack8(const f32x4& a, const f32x4& b) { u32x4 w; w.x = cvt_pk_bf16(a[0], a[1]); w.y = cvt_pk_bf16(a[2], a[3]); w.z = cvt_pk_bf16(b[0], b[1]); w.w = cvt_pk_bf16(b[2], b[3]); return w; }
;     __device__ __forceinline__ void operator()(const f32x4 (&acc)[2][2][4][2], const Unit& u, int wr, int wc, int fr, int fq) const {
;         const int row0 = u.pm * BM + wr * 64 + fr, col0 = u.pn * BM + wc * 32 + 8 * fq;
;         const float* gp = gate + (size_t)(u.pm >> 3) * 12288 + col0;
;         f32x4 gv[2][2];
; #pragma unroll
;         for (int bj = 0; bj < 2; ++bj)
; #pragma unroll
;             for (int n = 0; n < 2; ++n) { gv[bj][n] = *(const f32x4*)(gp + bj * HALF + n * 4); if (cscale) gv[bj][n] = gv[bj][n] * *(const f32x4*)(cscale + col0 + bj * HALF + n * 4); }
;     ...
;             for (int ai = 0; ai < 2; ++ai) { u32x4 xw[4][2];
; #pragma unroll
;                 for (int m = 0; m < 4; ++m)
; #pragma unroll
;                     for (int bj = 0; bj < 2; ++bj) xw[m][bj] = *(const u32x4*)((const bf16_t*)xin + (size_t)(row0 + ai * HALF + m * 16) * 2048 + col0 + bj * HALF);
; #pragma unroll
;                 for (int m = 0; m < 4; ++m)
; #pragma unroll
;                     for (int bj = 0; bj < 2; ++bj) { const u32x4 w = xw[m][bj];
;                         const f32x4 x0 = (f32x4){__builtin_bit_cast(float, w.x << 16), __builtin_bit_cast(float, w.x & 0xffff0000u), __builtin_bit_cast(float, w.y << 16), __builtin_bit_cast(float, w.y & 0xffff0000u)};
;                         const f32x4 x1 = (f32x4){__builtin_bit_cast(float, w.z << 16), __builtin_bit_cast(float, w.z & 0xffff0000u), __builtin_bit_cast(float, w.w << 16), __builtin_bit_cast(float, w.w & 0xffff0000u)};
;                         *(u32x4*)(xout + (size_t)(row0 + ai * HALF + m * 16) * 2048 + col0 + bj * HALF) = pack8(x0 + gv[bj][0] * acc[ai][bj][m][0], x1 + gv[bj][1] * acc[ai][bj][m][1]); }
.LBB0_2968:
	v_mov_b32_e32 v84, v252
	s_lshl_b32 s0, s80, 8
	v_ashrrev_i32_e32 v82, 1, v84
	s_or_b32 s0, s0, s70
	v_and_b32_e32 v82, -8, v82
	v_add_u32_e32 v82, s0, v82
	s_ashr_i32 s0, s79, 3
	s_mul_hi_i32 s1, s0, 0xc000
	s_mul_i32 s0, s0, 0xc000
	s_add_u32 s0, s67, s0
	s_addc_u32 s1, s68, s1
	s_lshl_b32 s33, s79, 8
	s_add_i32 s33, s33, s69
	v_ashrrev_i32_e32 v83, 31, v82
	v_and_or_b32 v146, v84, 15, s33
	v_lshlrev_b64 v[160:161], 1, v[82:83]
	v_ashrrev_i32_e32 v147, 31, v146
	v_lshl_add_u64 v[162:163], s[60:61], 0, v[160:161]
	v_lshlrev_b64 v[164:165], 12, v[146:147]
	v_or_b32_e32 v148, 16, v146
	v_lshl_add_u64 v[84:85], v[162:163], 0, v[164:165]
	v_ashrrev_i32_e32 v149, 31, v148
	global_load_dwordx4 v[172:175], v[84:85], off
	global_load_dwordx4 v[176:179], v[84:85], off offset:256
	v_lshl_add_u64 v[86:87], v[82:83], 2, s[0:1]
	v_lshlrev_b64 v[200:201], 12, v[148:149]
	global_load_dwordx4 v[102:105], v[86:87], off
	global_load_dwordx4 v[94:97], v[86:87], off offset:16
	global_load_dwordx4 v[82:85], v[86:87], off offset:528
	s_nop 0
	global_load_dwordx4 v[86:89], v[86:87], off offset:512
	v_lshl_add_u64 v[148:149], v[162:163], 0, v[200:201]
	global_load_dwordx4 v[180:183], v[148:149], off
	global_load_dwordx4 v[184:187], v[148:149], off offset:256
	v_or_b32_e32 v148, 32, v146
	v_ashrrev_i32_e32 v149, 31, v148
	v_lshlrev_b64 v[202:203], 12, v[148:149]
	v_lshl_add_u64 v[148:149], v[162:163], 0, v[202:203]
	global_load_dwordx4 v[188:191], v[148:149], off
	v_or_b32_e32 v146, 48, v146
	v_ashrrev_i32_e32 v147, 31, v146
	v_lshlrev_b64 v[166:167], 12, v[146:147]
	v_lshl_add_u64 v[146:147], s[60:61], 0, v[164:165]
	v_lshl_add_u64 v[204:205], v[162:163], 0, v[166:167]
	v_lshl_add_u64 v[206:207], v[146:147], 0, v[160:161]
	global_load_dwordx4 v[192:195], v[148:149], off offset:256
	global_load_dwordx4 v[196:199], v[204:205], off
	s_nop 0
	global_load_dwordx4 v[146:149], v[204:205], off offset:256
	s_mov_b64 s[0:1], 0x80000
	s_and_b64 vcc, exec, s[8:9]
	s_mov_b64 s[8:9], -1
	s_waitcnt vmcnt(0)
	v_lshlrev_b32_e32 v204, 16, v172
	v_and_b32_e32 v205, 0xffff0000, v172
	v_lshlrev_b32_e32 v172, 16, v173
	v_and_b32_e32 v173, 0xffff0000, v173
	v_lshlrev_b32_e32 v208, 16, v174
	v_and_b32_e32 v209, 0xffff0000, v174
	v_lshlrev_b32_e32 v174, 16, v175
	v_and_b32_e32 v175, 0xffff0000, v175
	v_lshlrev_b32_e32 v210, 16, v176
	v_and_b32_e32 v211, 0xffff0000, v176
	v_lshlrev_b32_e32 v176, 16, v177
	v_and_b32_e32 v177, 0xffff0000, v177
	v_lshlrev_b32_e32 v212, 16, v178
	v_and_b32_e32 v213, 0xffff0000, v178
	v_lshlrev_b32_e32 v178, 16, v179
	v_and_b32_e32 v179, 0xffff0000, v179
	v_pk_fma_f32 v[140:141], v[140:141], v[104:105], v[172:173]
	v_pk_fma_f32 v[136:137], v[136:137], v[96:97], v[174:175]
	v_pk_fma_f32 v[144:145], v[144:145], v[88:89], v[176:177]
	v_pk_fma_f32 v[172:173], v[132:133], v[84:85], v[178:179]
	v_lshlrev_b32_e32 v176, 16, v180
	v_and_b32_e32 v177, 0xffff0000, v180
	v_lshlrev_b32_e32 v178, 16, v181
	v_and_b32_e32 v179, 0xffff0000, v181
	v_lshlrev_b32_e32 v180, 16, v182
	v_and_b32_e32 v181, 0xffff0000, v182
	v_pk_fma_f32 v[138:139], v[138:139], v[102:103], v[204:205]
	v_pk_fma_f32 v[134:135], v[134:135], v[94:95], v[208:209]
	v_pk_fma_f32 v[142:143], v[142:143], v[86:87], v[210:211]
	v_pk_fma_f32 v[174:175], v[130:131], v[82:83], v[212:213]
	v_lshlrev_b32_e32 v182, 16, v183
	v_and_b32_e32 v183, 0xffff0000, v183
	v_cvt_pk_bf16_f32 v130, v138, v139
	v_cvt_pk_bf16_f32 v131, v140, v141
	v_cvt_pk_bf16_f32 v132, v134, v135
	v_cvt_pk_bf16_f32 v133, v136, v137
	v_pk_fma_f32 v[126:127], v[126:127], v[102:103], v[176:177]
	v_pk_fma_f32 v[136:137], v[122:123], v[94:95], v[180:181]
	global_store_dwordx4 v[206:207], v[130:133], off
	v_cvt_pk_bf16_f32 v122, v142, v143
	v_pk_fma_f32 v[134:135], v[124:125], v[96:97], v[182:183]
	v_cvt_pk_bf16_f32 v123, v144, v145
	v_cvt_pk_bf16_f32 v124, v174, v175
	v_cvt_pk_bf16_f32 v125, v172, v173
	global_store_dwordx4 v[206:207], v[122:125], off offset:256
	v_pk_fma_f32 v[128:129], v[128:129], v[104:105], v[178:179]
	v_lshlrev_b32_e32 v130, 16, v187
	v_cvt_pk_bf16_f32 v122, v126, v127
	v_lshl_add_u64 v[126:127], s[60:61], 0, v[200:201]
	v_cvt_pk_bf16_f32 v123, v128, v129
	v_cvt_pk_bf16_f32 v124, v136, v137
	v_cvt_pk_bf16_f32 v125, v134, v135
	v_lshl_add_u64 v[126:127], v[126:127], 0, v[160:161]
	global_store_dwordx4 v[126:127], v[122:125], off
	v_lshlrev_b32_e32 v128, 16, v186
	v_and_b32_e32 v129, 0xffff0000, v186
	v_lshlrev_b32_e32 v122, 16, v184
	v_and_b32_e32 v123, 0xffff0000, v184
	v_lshlrev_b32_e32 v124, 16, v185
	v_and_b32_e32 v125, 0xffff0000, v185
	v_and_b32_e32 v131, 0xffff0000, v187
	v_pk_fma_f32 v[120:121], v[120:121], v[88:89], v[124:125]
	v_pk_fma_f32 v[118:119], v[118:119], v[86:87], v[122:123]
	v_pk_fma_f32 v[122:123], v[116:117], v[84:85], v[130:131]
	v_pk_fma_f32 v[116:117], v[114:115], v[82:83], v[128:129]
	v_cvt_pk_bf16_f32 v114, v118, v119
	v_cvt_pk_bf16_f32 v115, v120, v121
	v_lshlrev_b32_e32 v118, 16, v190
	v_cvt_pk_bf16_f32 v116, v116, v117
	v_cvt_pk_bf16_f32 v117, v122, v123
	global_store_dwordx4 v[126:127], v[114:117], off offset:256
	v_and_b32_e32 v119, 0xffff0000, v190
	v_lshlrev_b32_e32 v120, 16, v191
	v_lshlrev_b32_e32 v114, 16, v188
	v_and_b32_e32 v115, 0xffff0000, v188
	v_and_b32_e32 v121, 0xffff0000, v191
	v_pk_fma_f32 v[110:111], v[110:111], v[102:103], v[114:115]
	v_lshlrev_b32_e32 v116, 16, v189
	v_and_b32_e32 v117, 0xffff0000, v189
	v_pk_fma_f32 v[114:115], v[108:109], v[96:97], v[120:121]
	v_pk_fma_f32 v[108:109], v[106:107], v[94:95], v[118:119]
	v_cvt_pk_bf16_f32 v106, v110, v111
	v_lshl_add_u64 v[110:111], s[60:61], 0, v[202:203]
	v_pk_fma_f32 v[112:113], v[112:113], v[104:105], v[116:117]
; __device__ __forceinline__ u32x4 pack8(const f32x4& a, const f32x4& b) { u32x4 w; w.x = cvt_pk_bf16(a[0], a[1]); w.y = cvt_pk_bf16(a[2], a[3]); w.z = cvt_pk_bf16(b[0], b[1]); w.w = cvt_pk_bf16(b[2], b[3]); return w; }
;     __device__ __forceinline__ void operator()(const f32x4 (&acc)[2][2][4][2], const Unit& u, int wr, int wc, int fr, int fq) const {
;     ...
;             for (int ai = 0; ai < 2; ++ai) { u32x4 xw[4][2];
; #pragma unroll
;                 for (int m = 0; m < 4; ++m)
; #pragma unroll
;                     for (int bj = 0; bj < 2; ++bj) xw[m][bj] = *(const u32x4*)((const bf16_t*)xin + (size_t)(row0 + ai * HALF + m * 16) * 2048 + col0 + bj * HALF);
; #pragma unroll
;                 for (int m = 0; m < 4; ++m)
; #pragma unroll
;                     for (int bj = 0; bj < 2; ++bj) { const u32x4 w = xw[m][bj];
;                         const f32x4 x0 = (f32x4){__builtin_bit_cast(float, w.x << 16), __builtin_bit_cast(float, w.x & 0xffff0000u), __builtin_bit_cast(float, w.y << 16), __builtin_bit_cast(float, w.y & 0xffff0000u)};
;                         const f32x4 x1 = (f32x4){__builtin_bit_cast(float, w.z << 16), __builtin_bit_cast(float, w.z & 0xffff0000u), __builtin_bit_cast(float, w.w << 16), __builtin_bit_cast(float, w.w & 0xffff0000u)};
;                         *(u32x4*)(xout + (size_t)(row0 + ai * HALF + m * 16) * 2048 + col0 + bj * HALF) = pack8(x0 + gv[bj][0] * acc[ai][bj][m][0], x1 + gv[bj][1] * acc[ai][bj][m][1]); }
;                 asm volatile("" ::: "memory"); }
	v_lshl_add_u64 v[110:111], v[110:111], 0, v[160:161]
	v_cvt_pk_bf16_f32 v107, v112, v113
	v_cvt_pk_bf16_f32 v108, v108, v109
	v_cvt_pk_bf16_f32 v109, v114, v115
	global_store_dwordx4 v[110:111], v[106:109], off
	v_lshlrev_b32_e32 v112, 16, v194
	v_and_b32_e32 v113, 0xffff0000, v194
	v_lshlrev_b32_e32 v106, 16, v192
	v_and_b32_e32 v107, 0xffff0000, v192
	v_lshlrev_b32_e32 v108, 16, v193
	v_and_b32_e32 v109, 0xffff0000, v193
	v_lshlrev_b32_e32 v114, 16, v195
	v_and_b32_e32 v115, 0xffff0000, v195
	v_pk_fma_f32 v[100:101], v[100:101], v[88:89], v[108:109]
	v_pk_fma_f32 v[98:99], v[98:99], v[86:87], v[106:107]
	v_pk_fma_f32 v[106:107], v[92:93], v[84:85], v[114:115]
	v_pk_fma_f32 v[92:93], v[90:91], v[82:83], v[112:113]
	v_cvt_pk_bf16_f32 v90, v98, v99
	v_cvt_pk_bf16_f32 v91, v100, v101
	v_lshlrev_b32_e32 v98, 16, v198
	v_cvt_pk_bf16_f32 v92, v92, v93
	v_cvt_pk_bf16_f32 v93, v106, v107
	global_store_dwordx4 v[110:111], v[90:93], off offset:256
	v_and_b32_e32 v99, 0xffff0000, v198
	v_lshlrev_b32_e32 v100, 16, v199
	v_lshlrev_b32_e32 v90, 16, v196
	v_and_b32_e32 v91, 0xffff0000, v196
	v_and_b32_e32 v101, 0xffff0000, v199
	v_pk_fma_f32 v[78:79], v[78:79], v[102:103], v[90:91]
	v_lshlrev_b32_e32 v92, 16, v197
	v_and_b32_e32 v93, 0xffff0000, v197
	v_pk_fma_f32 v[90:91], v[76:77], v[96:97], v[100:101]
	v_pk_fma_f32 v[76:77], v[74:75], v[94:95], v[98:99]
	v_cvt_pk_bf16_f32 v74, v78, v79
	v_lshl_add_u64 v[78:79], s[60:61], 0, v[166:167]
	v_pk_fma_f32 v[80:81], v[80:81], v[104:105], v[92:93]
	v_lshl_add_u64 v[78:79], v[78:79], 0, v[160:161]
	v_cvt_pk_bf16_f32 v75, v80, v81
	v_cvt_pk_bf16_f32 v76, v76, v77
	v_cvt_pk_bf16_f32 v77, v90, v91
	global_store_dwordx4 v[78:79], v[74:77], off
	v_lshlrev_b32_e32 v80, 16, v148
	v_and_b32_e32 v81, 0xffff0000, v148
	v_lshlrev_b32_e32 v74, 16, v146
	v_and_b32_e32 v75, 0xffff0000, v146
	v_lshlrev_b32_e32 v90, 16, v149
	v_and_b32_e32 v91, 0xffff0000, v149
	v_lshlrev_b32_e32 v76, 16, v147
	v_and_b32_e32 v77, 0xffff0000, v147
	v_pk_fma_f32 v[70:71], v[70:71], v[86:87], v[74:75]
	v_pk_fma_f32 v[74:75], v[68:69], v[84:85], v[90:91]
	v_pk_fma_f32 v[68:69], v[66:67], v[82:83], v[80:81]
	v_pk_fma_f32 v[72:73], v[72:73], v[88:89], v[76:77]
	v_cvt_pk_bf16_f32 v66, v70, v71
	v_lshl_add_u64 v[80:81], v[164:165], 0, s[0:1]
	v_cvt_pk_bf16_f32 v67, v72, v73
	v_cvt_pk_bf16_f32 v68, v68, v69
	v_cvt_pk_bf16_f32 v69, v74, v75
	global_store_dwordx4 v[78:79], v[66:69], off offset:256
	s_mov_b64 s[0:1], 0x90000
	v_lshl_add_u64 v[118:119], v[164:165], 0, s[0:1]
	v_lshl_add_u64 v[66:67], v[162:163], 0, v[80:81]
	global_load_dwordx4 v[76:79], v[66:67], off
	global_load_dwordx4 v[90:93], v[66:67], off offset:256
	v_lshl_add_u64 v[66:67], v[162:163], 0, v[118:119]
	global_load_dwordx4 v[98:101], v[66:67], off
	global_load_dwordx4 v[106:109], v[66:67], off offset:256
	s_mov_b64 s[0:1], 0xa0000
	v_lshl_add_u64 v[120:121], v[164:165], 0, s[0:1]
	v_lshl_add_u64 v[66:67], v[162:163], 0, v[120:121]
	global_load_dwordx4 v[110:113], v[66:67], off
	global_load_dwordx4 v[114:117], v[66:67], off offset:256
	v_lshl_add_u64 v[74:75], v[164:165], 0, s[30:31]
	v_lshl_add_u64 v[66:67], v[162:163], 0, v[74:75]
	global_load_dwordx4 v[70:73], v[66:67], off
	s_nop 0
	global_load_dwordx4 v[66:69], v[66:67], off offset:256
	s_waitcnt vmcnt(7)
	v_lshlrev_b32_e32 v122, 16, v76
	v_and_b32_e32 v123, 0xffff0000, v76
	v_lshlrev_b32_e32 v76, 16, v77
	v_and_b32_e32 v77, 0xffff0000, v77
	v_lshlrev_b32_e32 v124, 16, v78
	v_and_b32_e32 v125, 0xffff0000, v78
	v_lshlrev_b32_e32 v78, 16, v79
	v_and_b32_e32 v79, 0xffff0000, v79
	v_pk_fma_f32 v[62:63], v[62:63], v[102:103], v[122:123]
	v_pk_fma_f32 v[64:65], v[64:65], v[104:105], v[76:77]
	v_pk_fma_f32 v[76:77], v[60:61], v[96:97], v[78:79]
	v_pk_fma_f32 v[60:61], v[58:59], v[94:95], v[124:125]
	v_cvt_pk_bf16_f32 v58, v62, v63
	v_lshl_add_u64 v[62:63], s[60:61], 0, v[80:81]
	v_cvt_pk_bf16_f32 v59, v64, v65
	v_cvt_pk_bf16_f32 v60, v60, v61
	v_cvt_pk_bf16_f32 v61, v76, v77
	v_lshl_add_u64 v[62:63], v[62:63], 0, v[160:161]
	global_store_dwordx4 v[62:63], v[58:61], off
	s_waitcnt vmcnt(7)
	v_lshlrev_b32_e32 v64, 16, v92
	v_and_b32_e32 v65, 0xffff0000, v92
	v_lshlrev_b32_e32 v58, 16, v90
	v_and_b32_e32 v59, 0xffff0000, v90
	v_lshlrev_b32_e32 v60, 16, v91
	v_and_b32_e32 v61, 0xffff0000, v91
	v_lshlrev_b32_e32 v76, 16, v93
	v_and_b32_e32 v77, 0xffff0000, v93
	v_pk_fma_f32 v[56:57], v[56:57], v[88:89], v[60:61]
	v_pk_fma_f32 v[54:55], v[54:55], v[86:87], v[58:59]
	v_pk_fma_f32 v[58:59], v[52:53], v[84:85], v[76:77]
	v_pk_fma_f32 v[52:53], v[50:51], v[82:83], v[64:65]
	v_cvt_pk_bf16_f32 v50, v54, v55
	v_cvt_pk_bf16_f32 v51, v56, v57
	s_waitcnt vmcnt(6)
; __device__ __forceinline__ u32x4 pack8(const f32x4& a, const f32x4& b) { u32x4 w; w.x = cvt_pk_bf16(a[0], a[1]); w.y = cvt_pk_bf16(a[2], a[3]); w.z = cvt_pk_bf16(b[0], b[1]); w.w = cvt_pk_bf16(b[2], b[3]); return w; }
;     __device__ __forceinline__ void operator()(const f32x4 (&acc)[2][2][4][2], const Unit& u, int wr, int wc, int fr, int fq) const {
;     ...
;                 for (int m = 0; m < 4; ++m)
; #pragma unroll
;                     for (int bj = 0; bj < 2; ++bj) { const u32x4 w = xw[m][bj];
;                         const f32x4 x0 = (f32x4){__builtin_bit_cast(float, w.x << 16), __builtin_bit_cast(float, w.x & 0xffff0000u), __builtin_bit_cast(float, w.y << 16), __builtin_bit_cast(float, w.y & 0xffff0000u)};
;                         const f32x4 x1 = (f32x4){__builtin_bit_cast(float, w.z << 16), __builtin_bit_cast(float, w.z & 0xffff0000u), __builtin_bit_cast(float, w.w << 16), __builtin_bit_cast(float, w.w & 0xffff0000u)};
;                         *(u32x4*)(xout + (size_t)(row0 + ai * HALF + m * 16) * 2048 + col0 + bj * HALF) = pack8(x0 + gv[bj][0] * acc[ai][bj][m][0], x1 + gv[bj][1] * acc[ai][bj][m][1]); }
;                 asm volatile("" ::: "memory"); }
	v_lshlrev_b32_e32 v54, 16, v100
	v_cvt_pk_bf16_f32 v52, v52, v53
	v_cvt_pk_bf16_f32 v53, v58, v59
	global_store_dwordx4 v[62:63], v[50:53], off offset:256
	v_and_b32_e32 v55, 0xffff0000, v100
	v_lshlrev_b32_e32 v56, 16, v101
	v_lshlrev_b32_e32 v50, 16, v98
	v_and_b32_e32 v51, 0xffff0000, v98
	v_and_b32_e32 v57, 0xffff0000, v101
	v_pk_fma_f32 v[46:47], v[46:47], v[102:103], v[50:51]
	v_lshlrev_b32_e32 v52, 16, v99
	v_and_b32_e32 v53, 0xffff0000, v99
	v_pk_fma_f32 v[50:51], v[44:45], v[96:97], v[56:57]
	v_pk_fma_f32 v[44:45], v[42:43], v[94:95], v[54:55]
	v_cvt_pk_bf16_f32 v42, v46, v47
	v_lshl_add_u64 v[46:47], s[60:61], 0, v[118:119]
	v_pk_fma_f32 v[48:49], v[48:49], v[104:105], v[52:53]
	v_lshl_add_u64 v[46:47], v[46:47], 0, v[160:161]
	v_cvt_pk_bf16_f32 v43, v48, v49
	v_cvt_pk_bf16_f32 v44, v44, v45
	v_cvt_pk_bf16_f32 v45, v50, v51
	global_store_dwordx4 v[46:47], v[42:45], off
	s_waitcnt vmcnt(7)
	v_lshlrev_b32_e32 v48, 16, v108
	v_and_b32_e32 v49, 0xffff0000, v108
	v_lshlrev_b32_e32 v42, 16, v106
	v_and_b32_e32 v43, 0xffff0000, v106
	v_lshlrev_b32_e32 v44, 16, v107
	v_and_b32_e32 v45, 0xffff0000, v107
	v_lshlrev_b32_e32 v50, 16, v109
	v_and_b32_e32 v51, 0xffff0000, v109
	v_pk_fma_f32 v[40:41], v[40:41], v[88:89], v[44:45]
	v_pk_fma_f32 v[38:39], v[38:39], v[86:87], v[42:43]
	v_pk_fma_f32 v[42:43], v[36:37], v[84:85], v[50:51]
	v_pk_fma_f32 v[36:37], v[34:35], v[82:83], v[48:49]
	v_cvt_pk_bf16_f32 v34, v38, v39
	v_cvt_pk_bf16_f32 v35, v40, v41
	s_waitcnt vmcnt(6)
	v_lshlrev_b32_e32 v38, 16, v112
	v_cvt_pk_bf16_f32 v36, v36, v37
	v_cvt_pk_bf16_f32 v37, v42, v43
	global_store_dwordx4 v[46:47], v[34:37], off offset:256
	v_and_b32_e32 v39, 0xffff0000, v112
	v_lshlrev_b32_e32 v40, 16, v113
	v_lshlrev_b32_e32 v34, 16, v110
	v_and_b32_e32 v35, 0xffff0000, v110
	v_and_b32_e32 v41, 0xffff0000, v113
	v_pk_fma_f32 v[30:31], v[30:31], v[102:103], v[34:35]
	v_lshlrev_b32_e32 v36, 16, v111
	v_and_b32_e32 v37, 0xffff0000, v111
	v_pk_fma_f32 v[34:35], v[28:29], v[96:97], v[40:41]
	v_pk_fma_f32 v[28:29], v[26:27], v[94:95], v[38:39]
	v_cvt_pk_bf16_f32 v26, v30, v31
	v_lshl_add_u64 v[30:31], s[60:61], 0, v[120:121]
	v_pk_fma_f32 v[32:33], v[32:33], v[104:105], v[36:37]
	v_lshl_add_u64 v[30:31], v[30:31], 0, v[160:161]
	v_cvt_pk_bf16_f32 v27, v32, v33
	v_cvt_pk_bf16_f32 v28, v28, v29
	v_cvt_pk_bf16_f32 v29, v34, v35
	global_store_dwordx4 v[30:31], v[26:29], off
	s_waitcnt vmcnt(7)
	v_lshlrev_b32_e32 v32, 16, v116
	v_and_b32_e32 v33, 0xffff0000, v116
	v_lshlrev_b32_e32 v26, 16, v114
	v_and_b32_e32 v27, 0xffff0000, v114
	v_lshlrev_b32_e32 v28, 16, v115
	v_and_b32_e32 v29, 0xffff0000, v115
	v_lshlrev_b32_e32 v34, 16, v117
	v_and_b32_e32 v35, 0xffff0000, v117
	v_pk_fma_f32 v[24:25], v[24:25], v[88:89], v[28:29]
	v_pk_fma_f32 v[22:23], v[22:23], v[86:87], v[26:27]
	v_pk_fma_f32 v[26:27], v[20:21], v[84:85], v[34:35]
	v_pk_fma_f32 v[20:21], v[18:19], v[82:83], v[32:33]
	v_cvt_pk_bf16_f32 v18, v22, v23
	v_cvt_pk_bf16_f32 v19, v24, v25
	s_waitcnt vmcnt(6)
	v_lshlrev_b32_e32 v22, 16, v72
	v_cvt_pk_bf16_f32 v20, v20, v21
	v_cvt_pk_bf16_f32 v21, v26, v27
	global_store_dwordx4 v[30:31], v[18:21], off offset:256
	v_and_b32_e32 v23, 0xffff0000, v72
	v_lshlrev_b32_e32 v24, 16, v73
	v_lshlrev_b32_e32 v18, 16, v70
	v_and_b32_e32 v19, 0xffff0000, v70
	v_and_b32_e32 v25, 0xffff0000, v73
	v_pk_fma_f32 v[14:15], v[14:15], v[102:103], v[18:19]
	v_lshlrev_b32_e32 v20, 16, v71
	v_and_b32_e32 v21, 0xffff0000, v71
	v_pk_fma_f32 v[18:19], v[12:13], v[96:97], v[24:25]
	v_pk_fma_f32 v[12:13], v[10:11], v[94:95], v[22:23]
	v_cvt_pk_bf16_f32 v10, v14, v15
	v_lshl_add_u64 v[14:15], s[60:61], 0, v[74:75]
	v_pk_fma_f32 v[16:17], v[16:17], v[104:105], v[20:21]
	v_lshl_add_u64 v[14:15], v[14:15], 0, v[160:161]
	v_cvt_pk_bf16_f32 v11, v16, v17
	v_cvt_pk_bf16_f32 v12, v12, v13
	v_cvt_pk_bf16_f32 v13, v18, v19
	global_store_dwordx4 v[14:15], v[10:13], off
	s_waitcnt vmcnt(7)
	v_lshlrev_b32_e32 v16, 16, v68
	v_and_b32_e32 v17, 0xffff0000, v68
	v_lshlrev_b32_e32 v10, 16, v66
	v_and_b32_e32 v11, 0xffff0000, v66
	v_lshlrev_b32_e32 v18, 16, v69
	v_and_b32_e32 v19, 0xffff0000, v69
	v_lshlrev_b32_e32 v12, 16, v67
	v_and_b32_e32 v13, 0xffff0000, v67
	v_pk_fma_f32 v[6:7], v[6:7], v[86:87], v[10:11]
	v_pk_fma_f32 v[10:11], v[4:5], v[84:85], v[18:19]
	v_pk_fma_f32 v[4:5], v[2:3], v[82:83], v[16:17]
	v_pk_fma_f32 v[8:9], v[8:9], v[88:89], v[12:13]
	v_cvt_pk_bf16_f32 v2, v6, v7
	s_nop 0
	v_cvt_pk_bf16_f32 v3, v8, v9
	v_cvt_pk_bf16_f32 v4, v4, v5
	v_cvt_pk_bf16_f32 v5, v10, v11
	global_store_dwordx4 v[14:15], v[2:5], off offset:256
	s_cbranch_vccnz .LBB0_2953
	s_and_b64 vcc, exec, s[6:7]
	s_cbranch_vccnz .LBB0_2952
	s_barrier
	s_branch .LBB0_2952

; __global__ void __launch_bounds__(NWAVES * 64, 2) fwd_kernel(Args args_byval) {
;     (void)args_byval; const Args& args = *(const Args*)__builtin_amdgcn_kernarg_segment_ptr();
	.amdhsa_kernel _Z10fwd_kernel4Args
		.amdhsa_group_segment_fixed_size 0
		.amdhsa_private_segment_fixed_size 0
		.amdhsa_kernarg_size 448
		.amdhsa_user_sgpr_count 2
		.amdhsa_user_sgpr_dispatch_ptr 0
		.amdhsa_user_sgpr_queue_ptr 0
		.amdhsa_user_sgpr_kernarg_segment_ptr 1
		.amdhsa_user_sgpr_dispatch_id 0
		.amdhsa_user_sgpr_kernarg_preload_length 0
		.amdhsa_user_sgpr_kernarg_preload_offset 0
		.amdhsa_user_sgpr_private_segment_size 0
		.amdhsa_uses_dynamic_stack 0
		.amdhsa_enable_private_segment 0
		.amdhsa_system_sgpr_workgroup_id_x 1
		.amdhsa_system_sgpr_workgroup_id_y 0
		.amdhsa_system_sgpr_workgroup_id_z 0
		.amdhsa_system_sgpr_workgroup_info 0
		.amdhsa_system_vgpr_workitem_id 0
		.amdhsa_next_free_vgpr 256
		.amdhsa_next_free_sgpr 98
		.amdhsa_accum_offset 256
		.amdhsa_reserve_vcc 1
		.amdhsa_float_round_mode_32 0
		.amdhsa_float_round_mode_16_64 0
		.amdhsa_float_denorm_mode_32 3
		.amdhsa_float_denorm_mode_16_64 3
		.amdhsa_dx10_clamp 1
		.amdhsa_ieee_mode 1
		.amdhsa_fp16_overflow 0
		.amdhsa_tg_split 0
		.amdhsa_exception_fp_ieee_invalid_op 0
		.amdhsa_exception_fp_denorm_src 0
		.amdhsa_exception_fp_ieee_div_zero 0
		.amdhsa_exception_fp_ieee_overflow 0
		.amdhsa_exception_fp_ieee_underflow 0
		.amdhsa_exception_fp_ieee_inexact 0
		.amdhsa_exception_int_div_zero 0
	.end_amdhsa_kernel

; __global__ void __launch_bounds__(NWAVES * 64, 2) fwd_kernel(Args args_byval) {
;     (void)args_byval; const Args& args = *(const Args*)__builtin_amdgcn_kernarg_segment_ptr();
amdhsa.kernels:
  - .agpr_count:     0
    .args:
      - .offset:         0
        .size:           192
        .value_kind:     by_value
      - .offset:         192
        .size:           4
        .value_kind:     hidden_block_count_x
      - .offset:         196
        .size:           4
        .value_kind:     hidden_block_count_y
      - .offset:         200
        .size:           4
        .value_kind:     hidden_block_count_z
      - .offset:         204
        .size:           2
        .value_kind:     hidden_group_size_x
      - .offset:         206
        .size:           2
        .value_kind:     hidden_group_size_y
      - .offset:         208
        .size:           2
        .value_kind:     hidden_group_size_z
      - .offset:         210
        .size:           2
        .value_kind:     hidden_remainder_x
      - .offset:         212
        .size:           2
        .value_kind:     hidden_remainder_y
      - .offset:         214
        .size:           2
        .value_kind:     hidden_remainder_z
      - .offset:         232
        .size:           8
        .value_kind:     hidden_global_offset_x
      - .offset:         240
        .size:           8
        .value_kind:     hidden_global_offset_y
      - .offset:         248
        .size:           8
        .value_kind:     hidden_global_offset_z
      - .offset:         256
        .size:           2
        .value_kind:     hidden_grid_dims
      - .offset:         312
        .size:           4
        .value_kind:     hidden_dynamic_lds_size
    .group_segment_fixed_size: 0
    .kernarg_segment_align: 8
    .kernarg_segment_size: 448
    .language:       OpenCL C
    .language_version:
      - 2
      - 0
    .max_flat_workgroup_size: 512
    .name:           _Z10fwd_kernel4Args
    .private_segment_fixed_size: 0
    .sgpr_count:     104
    .sgpr_spill_count: 28
    .symbol:         _Z10fwd_kernel4Args.kd
    .uniform_work_group_size: 1
    .uses_dynamic_stack: false
    .vgpr_count:     256
    .vgpr_spill_count: 0
    .wavefront_size: 64
